# attention tile-A/diag chunks keep scores in MFMA registers (8 phi copies per chunk removed), P2 conv stage packed f32 ops expanded + product/add chains fused to fma + operand copies propagated
# speedup vs baseline: 1.0060x; 1.0001x over previous
; __device__ __forceinline__ float bflo(unsigned w) { return __uint_as_float(w << 16); }
; __device__ __forceinline__ float bfhi(unsigned w) { return __uint_as_float(w & 0xffff0000u); }
; __device__ __forceinline__ void gdn_prep_item(const Params& p, unsigned char* lds, int item, u32x4 (&raw)[3][2][4], float& gpre, float& bpre, int next_item) {
;     ...
;         for (int sec = 0; sec < 3; ++sec) {
; #pragma unroll
;             for (int ps = 0; ps < 2; ++ps) {
;                 const int i = 32 * ps + (tid >> 4);
;                 float y[8];
; #pragma unroll
;                 for (int e = 0; e < 8; ++e) y[e] = 0.f;
; #pragma unroll
;                 for (int j = 0; j < 4; ++j) { const u32x4 w = raw[sec][ps][j];
;                     const f32x4 c0 = *(const f32x4*)(cwl + (j * 3 + sec) * 128 + 8 * grp), c1 = *(const f32x4*)(cwl + (j * 3 + sec) * 128 + 8 * grp + 4);
;                     y[0] += c0[0] * bflo(w.x); y[1] += c0[1] * bfhi(w.x); y[2] += c0[2] * bflo(w.y); y[3] += c0[3] * bfhi(w.y);
;                     y[4] += c1[0] * bflo(w.z); y[5] += c1[1] * bfhi(w.z); y[6] += c1[2] * bflo(w.w); y[7] += c1[3] * bfhi(w.w); }
; #pragma unroll
;                 for (int e = 0; e < 8; ++e) y[e] = y[e] * __builtin_amdgcn_rcpf(1.f + __expf(-y[e]));
;                 const float gci = gcs[i], bi = bets[i];
;                 if (sec < 2) {
;                     float ss = 0.f;
; #pragma unroll
;                     for (int e = 0; e < 8; ++e) ss += y[e] * y[e];
; #pragma unroll
;                     for (int o = 1; o < 16; o <<= 1) ss += __shfl_xor(ss, o);
;                     const float rn = rsqrtf(ss + RMS_EPS);
.LBB0_106:
	s_or_b64 exec, exec, s[20:21]
	v_add_u32_e32 v0, 0, v142
	s_waitcnt lgkmcnt(0)
	s_barrier
	v_add_u32_e32 v17, 0x23e00, v0
	ds_read_b128 v[8:11], v17
	ds_read_b128 v[0:3], v17 offset:16
	ds_read_b128 v[12:15], v17 offset:1536
	ds_read_b128 v[4:7], v17 offset:1552
	s_waitcnt vmcnt(15)
	v_lshlrev_b32_e32 v19, 16, v20
	v_lshlrev_b32_e32 v18, 16, v24
	s_waitcnt lgkmcnt(3)
	s_waitcnt lgkmcnt(1)
	v_mul_f32_e32 v18, v8, v18
	v_fma_f32 v19, v12, v19, v18
	v_and_b32_e32 v177, 0xffff0000, v20
	v_and_b32_e32 v176, 0xffff0000, v24
	v_mul_f32_e32 v176, v9, v176
	v_fma_f32 v177, v13, v177, v176
	v_lshlrev_b32_e32 v9, 16, v21
	v_lshlrev_b32_e32 v8, 16, v25
	v_mul_f32_e32 v178, v10, v8
	v_fma_f32 v179, v14, v9, v178
	v_and_b32_e32 v9, 0xffff0000, v21
	v_and_b32_e32 v8, 0xffff0000, v25
	v_mul_f32_e32 v180, v11, v8
	v_fma_f32 v181, v15, v9, v180
	v_lshlrev_b32_e32 v13, 16, v22
	v_lshlrev_b32_e32 v12, 16, v26
	s_waitcnt lgkmcnt(0)
	v_mul_f32_e32 v182, v0, v12
	v_fma_f32 v183, v4, v13, v182
	v_and_b32_e32 v13, 0xffff0000, v22
	v_and_b32_e32 v12, 0xffff0000, v26
	v_mov_b32_e32 v174, s92
	v_mul_f32_e32 v184, v1, v12
	v_fma_f32 v185, v5, v13, v184
	v_lshlrev_b32_e32 v1, 16, v23
	v_lshlrev_b32_e32 v0, 16, v27
	ds_read_b32 v174, v174
	ds_read_b128 v[8:11], v17 offset:3072
	v_mul_f32_e32 v186, v2, v0
	v_fma_f32 v187, v6, v1, v186
	v_and_b32_e32 v1, 0xffff0000, v23
	v_and_b32_e32 v0, 0xffff0000, v27
	v_mul_f32_e32 v188, v3, v0
	v_fma_f32 v189, v7, v1, v188
	ds_read_b128 v[0:3], v17 offset:3088
	ds_read_b128 v[4:7], v17 offset:4608
	ds_read_b128 v[12:15], v17 offset:4624
	s_waitcnt vmcnt(14)
	v_lshlrev_b32_e32 v191, 16, v32
	v_lshlrev_b32_e32 v190, 16, v28
	s_waitcnt lgkmcnt(3)
	s_waitcnt lgkmcnt(1)
	v_fma_f32 v190, v8, v190, v19
	v_fma_f32 v191, v4, v191, v190
	v_and_b32_e32 v193, 0xffff0000, v32
	v_and_b32_e32 v192, 0xffff0000, v28
	v_fma_f32 v4, v9, v192, v177
	v_fma_f32 v5, v5, v193, v4
	v_lshlrev_b32_e32 v9, 16, v33
	v_lshlrev_b32_e32 v8, 16, v29
	v_fma_f32 v8, v10, v8, v179
	v_fma_f32 v9, v6, v9, v8
	v_and_b32_e32 v193, 0xffff0000, v33
	v_and_b32_e32 v192, 0xffff0000, v29
	v_fma_f32 v6, v11, v192, v181
	v_fma_f32 v6, v7, v193, v6
	v_lshlrev_b32_e32 v11, 16, v34
	v_lshlrev_b32_e32 v10, 16, v30
	s_waitcnt lgkmcnt(0)
	v_fma_f32 v10, v0, v10, v183
	v_fma_f32 v11, v12, v11, v10
	v_and_b32_e32 v193, 0xffff0000, v34
	v_and_b32_e32 v192, 0xffff0000, v30
	v_fma_f32 v0, v1, v192, v185
	v_fma_f32 v0, v13, v193, v0
	v_lshlrev_b32_e32 v13, 16, v35
	v_lshlrev_b32_e32 v12, 16, v31
	v_fma_f32 v12, v2, v12, v187
	v_fma_f32 v13, v14, v13, v12
	v_and_b32_e32 v19, 0xffff0000, v35
	v_mul_f32_e32 v2, 0xbfb8aa3b, v191
	v_exp_f32_e32 v2, v2
	v_mul_f32_e32 v14, 0xbfb8aa3b, v5
	v_exp_f32_e32 v14, v14
	v_and_b32_e32 v18, 0xffff0000, v31
	v_add_f32_e32 v2, 1.0, v2
	v_rcp_f32_e32 v176, v2
	v_add_f32_e32 v2, 1.0, v14
	v_rcp_f32_e32 v177, v2
	v_fma_f32 v2, v3, v18, v189
	v_fma_f32 v2, v15, v19, v2
	v_mul_f32_e32 v8, 0xbfb8aa3b, v9
	v_exp_f32_e32 v14, v8
	v_mul_f32_e32 v8, 0xbfb8aa3b, v6
	v_exp_f32_e32 v18, v8
	v_add_f32_e32 v14, 1.0, v14
	v_rcp_f32_e32 v15, v14
	v_add_f32_e32 v14, 1.0, v18
	v_mul_f32_e32 v4, v191, v176
	v_mul_f32_e32 v5, v5, v177
	v_mov_b32_e32 v1, v11
	v_rcp_f32_e32 v14, v14
	v_mul_f32_e32 v10, 0xbfb8aa3b, v11
	v_exp_f32_e32 v18, v10
	v_mul_f32_e32 v10, 0xbfb8aa3b, v0
	v_exp_f32_e32 v19, v10
	v_mul_f32_e32 v10, v6, v14
	v_mul_f32_e32 v11, v9, v15
	v_add_f32_e32 v6, 1.0, v18
	v_rcp_f32_e32 v7, v6
	v_add_f32_e32 v6, 1.0, v19
	v_mov_b32_e32 v3, v13
	v_rcp_f32_e32 v6, v6
	v_mul_f32_e32 v12, 0xbfb8aa3b, v13
	v_exp_f32_e32 v12, v12
	v_mul_f32_e32 v13, 0xbfb8aa3b, v2
	v_exp_f32_e32 v14, v13
	v_mul_f32_e32 v8, v4, v4
	v_mul_f32_e32 v9, v5, v5
	v_add_f32_e32 v12, 1.0, v12
	v_rcp_f32_e32 v13, v12
	v_add_f32_e32 v12, 1.0, v14
	v_rcp_f32_e32 v12, v12
	v_mul_f32_e32 v14, v10, v10
	v_mul_f32_e32 v15, v11, v11
	v_add_f32_e32 v8, v8, v9
	v_mul_f32_e32 v0, v0, v6
	v_mul_f32_e32 v1, v1, v7
	v_add_f32_e32 v8, v15, v8
	v_mul_f32_e32 v6, v0, v0
	v_mul_f32_e32 v7, v1, v1
	v_add_f32_e32 v8, v14, v8
	v_mul_f32_e32 v2, v2, v12
	v_mul_f32_e32 v3, v3, v13
	v_add_f32_e32 v7, v7, v8
	v_mul_f32_e32 v12, v2, v2
	v_mul_f32_e32 v13, v3, v3
	v_add_f32_e32 v6, v6, v7
	v_add_f32_e32 v6, v13, v6
	v_add_f32_e32 v7, v12, v6
	v_and_b32_e32 v6, 64, v163
	v_add_u32_e32 v9, 64, v6
	v_xor_b32_e32 v6, 1, v163
	v_cmp_lt_i32_e32 vcc, v6, v9
	s_waitcnt vmcnt(10)
	v_lshlrev_b32_e32 v199, 16, v48
	v_lshlrev_b32_e32 v198, 16, v44
	v_cndmask_b32_e32 v6, v163, v6, vcc
	v_lshlrev_b32_e32 v6, 2, v6
	ds_bpermute_b32 v8, v6, v7
	s_waitcnt lgkmcnt(0)
	v_add_f32_e32 v8, v7, v8
	v_xor_b32_e32 v7, 2, v163
	v_cmp_lt_i32_e32 vcc, v7, v9
	s_nop 1
	v_cndmask_b32_e32 v7, v163, v7, vcc
	v_lshlrev_b32_e32 v7, 2, v7
	ds_bpermute_b32 v12, v7, v8
	s_waitcnt lgkmcnt(0)
	v_add_f32_e32 v12, v8, v12
	v_xor_b32_e32 v8, 4, v163
	v_cmp_lt_i32_e32 vcc, v8, v9
	s_nop 1
	v_cndmask_b32_e32 v8, v163, v8, vcc
	v_lshlrev_b32_e32 v8, 2, v8
	ds_bpermute_b32 v13, v8, v12
	s_waitcnt lgkmcnt(0)
	v_add_f32_e32 v12, v12, v13
	v_xor_b32_e32 v13, 8, v163
	v_cmp_lt_i32_e32 vcc, v13, v9
	s_nop 1
	v_cndmask_b32_e32 v9, v163, v13, vcc
	v_lshlrev_b32_e32 v9, 2, v9
	ds_bpermute_b32 v13, v9, v12
	s_waitcnt lgkmcnt(0)
	v_add_f32_e32 v12, v12, v13
	v_add_f32_e32 v12, 0x358637bd, v12
	v_mul_f32_e32 v13, 0x4b800000, v12
	v_cmp_gt_f32_e32 vcc, s93, v12
	s_nop 1
	v_cndmask_b32_e32 v12, v12, v13, vcc
	ds_read_b32 v13, v143
	v_rsq_f32_e32 v12, v12
	s_waitcnt lgkmcnt(0)
; __device__ __forceinline__ unsigned cvt_pk_bf16(float lo, float hi) { unsigned r; asm volatile("v_cvt_pk_bf16_f32 %0, %1, %2" : "=v"(r) : "v"(lo), "v"(hi)); return r; }
; __device__ __forceinline__ float bflo(unsigned w) { return __uint_as_float(w << 16); }
; __device__ __forceinline__ float bfhi(unsigned w) { return __uint_as_float(w & 0xffff0000u); }
; __device__ __forceinline__ void gdn_prep_item(const Params& p, unsigned char* lds, int item, u32x4 (&raw)[3][2][4], float& gpre, float& bpre, int next_item) {
;     ...
;                 for (int j = 0; j < 4; ++j) { const u32x4 w = raw[sec][ps][j];
;                     const f32x4 c0 = *(const f32x4*)(cwl + (j * 3 + sec) * 128 + 8 * grp), c1 = *(const f32x4*)(cwl + (j * 3 + sec) * 128 + 8 * grp + 4);
;                     y[0] += c0[0] * bflo(w.x); y[1] += c0[1] * bfhi(w.x); y[2] += c0[2] * bflo(w.y); y[3] += c0[3] * bfhi(w.y);
;                     y[4] += c1[0] * bflo(w.z); y[5] += c1[1] * bfhi(w.z); y[6] += c1[2] * bflo(w.w); y[7] += c1[3] * bfhi(w.w); }
; #pragma unroll
;                 for (int e = 0; e < 8; ++e) y[e] = y[e] * __builtin_amdgcn_rcpf(1.f + __expf(-y[e]));
;                 const float gci = gcs[i], bi = bets[i];
;                 if (sec < 2) {
;                     float ss = 0.f;
; #pragma unroll
;                     for (int e = 0; e < 8; ++e) ss += y[e] * y[e];
; #pragma unroll
;                     for (int o = 1; o < 16; o <<= 1) ss += __shfl_xor(ss, o);
;                     const float rn = rsqrtf(ss + RMS_EPS);
;                     if (sec == 0) {
;                         const float sc = rn * 0.08838834764831845f, eg = __expf(gci);
; #pragma unroll
;                         for (int e = 0; e < 8; ++e) y[e] *= sc;
;                         u32x4 w; w.x = cvt_pk_bf16(y[0], y[1]); w.y = cvt_pk_bf16(y[2], y[3]); w.z = cvt_pk_bf16(y[4], y[5]); w.w = cvt_pk_bf16(y[6], y[7]);
;                         *(u32x4*)(qb + i * 136 + 8 * grp) = w;
;                         u32x2 lo, hi; lo.x = cvt_pk_bf16(y[0] * eg, y[1] * eg); lo.y = cvt_pk_bf16(y[2] * eg, y[3] * eg); hi.x = cvt_pk_bf16(y[4] * eg, y[5] * eg); hi.y = cvt_pk_bf16(y[6] * eg, y[7] * eg);
;                         bf16_t* qd = (bf16_t*)(rec + 16384) + i * 128 + 16 * a16;
;                         *(u32x2*)(qd + 4 * bb) = lo; *(u32x2*)(qd + 8 + 4 * bb) = hi;
	v_mul_f32_e32 v13, 0x3fb8aa3b, v13
	v_mul_f32_e32 v14, 0x45800000, v12
	v_exp_f32_e32 v13, v13
	v_cndmask_b32_e32 v12, v12, v14, vcc
	v_mul_f32_e32 v12, 0x3db504f3, v12
	v_mul_f32_e32 v4, v4, v12
	v_mul_f32_e32 v5, v5, v12
	v_mul_f32_e32 v11, v11, v12
	v_mul_f32_e32 v10, v10, v12
	v_mul_f32_e32 v14, v1, v12
	v_mul_f32_e32 v15, v0, v12
	v_cvt_pk_bf16_f32 v0, v4, v5
	v_cvt_pk_bf16_f32 v1, v11, v10
	v_mul_f32_e32 v18, v3, v12
	v_mul_f32_e32 v12, v2, v12
	v_cvt_pk_bf16_f32 v2, v14, v15
	v_cvt_pk_bf16_f32 v3, v18, v12
	ds_write_b128 v155, v[0:3]
	v_mul_f32_e32 v0, v13, v4
	v_mul_f32_e32 v1, v13, v5
	v_cvt_pk_bf16_f32 v2, v0, v1
	v_mul_f32_e32 v0, v13, v11
	v_mul_f32_e32 v1, v13, v10
	v_cvt_pk_bf16_f32 v3, v0, v1
	v_mul_f32_e32 v0, v13, v14
	v_mul_f32_e32 v1, v13, v15
	v_cvt_pk_bf16_f32 v4, v0, v1
	v_mul_f32_e32 v0, v13, v18
	v_mul_f32_e32 v1, v13, v12
	v_cvt_pk_bf16_f32 v5, v0, v1
	ds_read_b128 v[10:13], v17
	ds_read_b128 v[176:179], v17 offset:16
	ds_read_b128 v[180:183], v17 offset:1536
	ds_read_b128 v[184:187], v17 offset:1552
	v_lshlrev_b32_e32 v1, 16, v40
	v_lshlrev_b32_e32 v0, 16, v36
	s_waitcnt lgkmcnt(3)
	s_waitcnt lgkmcnt(1)
	v_mul_f32_e32 v0, v10, v0
	v_mul_f32_e32 v1, v180, v1
	v_and_b32_e32 v15, 0xffff0000, v36
	v_and_b32_e32 v14, 0xffff0000, v40
	v_mov_b32_e32 v10, v181
	v_lshlrev_b32_e32 v181, 16, v42
	v_lshlrev_b32_e32 v180, 16, v38
	s_waitcnt lgkmcnt(0)
	v_mul_f32_e32 v14, v10, v14
	v_fma_f32 v15, v11, v15, v14
	v_lshlrev_b32_e32 v11, 16, v37
	v_lshlrev_b32_e32 v10, 16, v41
	v_mul_f32_e32 v190, v176, v180
	v_fma_f32 v191, v184, v181, v190
	v_and_b32_e32 v181, 0xffff0000, v42
	v_and_b32_e32 v180, 0xffff0000, v38
	v_mul_f32_e32 v18, v182, v10
	v_fma_f32 v19, v12, v11, v18
	v_and_b32_e32 v11, 0xffff0000, v37
	v_and_b32_e32 v10, 0xffff0000, v41
	v_mul_f32_e32 v192, v177, v180
	v_fma_f32 v193, v185, v181, v192
	v_lshlrev_b32_e32 v177, 16, v43
	v_lshlrev_b32_e32 v176, 16, v39
	ds_read_b32 v175, v145
	v_mul_f32_e32 v188, v183, v10
	v_fma_f32 v189, v13, v11, v188
	ds_read_b128 v[10:13], v17 offset:3072
	v_mul_f32_e32 v194, v178, v176
	v_fma_f32 v195, v186, v177, v194
	v_and_b32_e32 v177, 0xffff0000, v43
	v_and_b32_e32 v176, 0xffff0000, v39
	v_mul_f32_e32 v196, v179, v176
	v_fma_f32 v197, v187, v177, v196
	ds_read_b128 v[176:179], v17 offset:3088
	ds_read_b128 v[180:183], v17 offset:4608
	ds_read_b128 v[184:187], v17 offset:4624
	s_waitcnt lgkmcnt(3)
	s_waitcnt lgkmcnt(1)
	v_mul_f32_e32 v198, v10, v198
	v_mul_f32_e32 v199, v180, v199
	v_and_b32_e32 v201, 0xffff0000, v48
	v_and_b32_e32 v200, 0xffff0000, v44
	v_fma_f32 v10, v11, v200, v15
	v_fma_f32 v11, v181, v201, v10
	v_lshlrev_b32_e32 v181, 16, v49
	v_lshlrev_b32_e32 v180, 16, v45
	v_fma_f32 v180, v12, v180, v19
	v_fma_f32 v181, v182, v181, v180
	v_and_b32_e32 v201, 0xffff0000, v49
	v_and_b32_e32 v200, 0xffff0000, v45
	v_fma_f32 v12, v13, v200, v189
	v_fma_f32 v13, v183, v201, v12
	v_lshlrev_b32_e32 v183, 16, v50
	v_lshlrev_b32_e32 v182, 16, v46
	s_waitcnt lgkmcnt(0)
	v_fma_f32 v182, v176, v182, v191
	v_fma_f32 v183, v184, v183, v182
	v_and_b32_e32 v201, 0xffff0000, v50
	v_and_b32_e32 v200, 0xffff0000, v46
	v_fma_f32 v176, v177, v200, v193
	v_fma_f32 v176, v185, v201, v176
	v_lshlrev_b32_e32 v185, 16, v51
	v_lshlrev_b32_e32 v184, 16, v47
	v_fma_f32 v184, v178, v184, v195
	v_fma_f32 v185, v186, v185, v184
	v_add_f32_e32 v200, 0, v0
	v_add_f32_e32 v0, v200, v1
	v_add_f32_e32 v0, v0, v198
	v_add_f32_e32 v0, v0, v199
	v_mov_b32_e32 v1, v11
	v_mul_f32_e32 v10, 0xbfb8aa3b, v0
	v_exp_f32_e32 v10, v10
	v_mul_f32_e32 v11, 0xbfb8aa3b, v11
	v_exp_f32_e32 v15, v11
	v_add_f32_e32 v10, 1.0, v10
	v_rcp_f32_e32 v14, v10
	v_add_f32_e32 v10, 1.0, v15
	v_rcp_f32_e32 v15, v10
	v_and_b32_e32 v11, 0xffff0000, v51
	v_and_b32_e32 v10, 0xffff0000, v47
	v_mul_f32_e32 v14, v0, v14
	v_mul_f32_e32 v15, v1, v15
	v_mul_f32_e32 v12, 0xbfb8aa3b, v181
	v_exp_f32_e32 v18, v12
	v_mul_f32_e32 v12, 0xbfb8aa3b, v13
	v_exp_f32_e32 v178, v12
	v_add_f32_e32 v18, 1.0, v18
	v_rcp_f32_e32 v19, v18
	v_add_f32_e32 v18, 1.0, v178
	v_rcp_f32_e32 v18, v18
	v_fma_f32 v10, v179, v10, v197
	v_fma_f32 v10, v187, v11, v10
	v_mul_f32_e32 v18, v13, v18
	v_mul_f32_e32 v19, v181, v19
	v_mul_f32_e32 v178, 0xbfb8aa3b, v183
	v_exp_f32_e32 v178, v178
	v_mul_f32_e32 v179, 0xbfb8aa3b, v176
	v_exp_f32_e32 v179, v179
	v_add_f32_e32 v0, 1.0, v178
	v_rcp_f32_e32 v1, v0
	v_add_f32_e32 v0, 1.0, v179
	v_rcp_f32_e32 v0, v0
	v_mul_f32_e32 v178, 0xbfb8aa3b, v185
	v_exp_f32_e32 v178, v178
	v_mul_f32_e32 v179, 0xbfb8aa3b, v10
	v_exp_f32_e32 v180, v179
	v_mul_f32_e32 v12, v14, v14
	v_mul_f32_e32 v13, v15, v15
	v_add_f32_e32 v178, 1.0, v178
	v_rcp_f32_e32 v179, v178
	v_add_f32_e32 v178, 1.0, v180
	v_rcp_f32_e32 v178, v178
	v_mul_f32_e32 v180, v18, v18
	v_mul_f32_e32 v181, v19, v19
	v_add_f32_e32 v12, v12, v13
	v_mul_f32_e32 v176, v176, v0
	v_mul_f32_e32 v177, v183, v1
	v_add_f32_e32 v12, v181, v12
	v_mul_f32_e32 v0, v176, v176
	v_mul_f32_e32 v1, v177, v177
	v_add_f32_e32 v12, v180, v12
	v_mul_f32_e32 v10, v10, v178
	v_mul_f32_e32 v11, v185, v179
	v_add_f32_e32 v1, v1, v12
	v_mul_f32_e32 v178, v10, v10
	v_mul_f32_e32 v179, v11, v11
	v_add_f32_e32 v0, v0, v1
	v_add_f32_e32 v0, v179, v0
	v_add_f32_e32 v0, v178, v0
	ds_bpermute_b32 v1, v6, v0
	s_waitcnt vmcnt(9)
	v_lshlrev_b32_e32 v201, 16, v64
	v_lshlrev_b32_e32 v200, 16, v60
	s_waitcnt lgkmcnt(0)
	v_add_f32_e32 v0, v0, v1
	ds_bpermute_b32 v1, v7, v0
	s_waitcnt lgkmcnt(0)
	v_add_f32_e32 v0, v0, v1
	ds_bpermute_b32 v1, v8, v0
	s_waitcnt lgkmcnt(0)
	v_add_f32_e32 v12, v0, v1
	ds_bpermute_b32 v13, v9, v12
	v_lshl_add_u64 v[0:1], v[120:121], 0, s[86:87]
	s_waitcnt lgkmcnt(0)
; __device__ __forceinline__ unsigned cvt_pk_bf16(float lo, float hi) { unsigned r; asm volatile("v_cvt_pk_bf16_f32 %0, %1, %2" : "=v"(r) : "v"(lo), "v"(hi)); return r; }
; __device__ __forceinline__ float bflo(unsigned w) { return __uint_as_float(w << 16); }
; __device__ __forceinline__ float bfhi(unsigned w) { return __uint_as_float(w & 0xffff0000u); }
; __device__ __forceinline__ void gdn_prep_item(const Params& p, unsigned char* lds, int item, u32x4 (&raw)[3][2][4], float& gpre, float& bpre, int next_item) {
;     ...
;                 for (int j = 0; j < 4; ++j) { const u32x4 w = raw[sec][ps][j];
;                     const f32x4 c0 = *(const f32x4*)(cwl + (j * 3 + sec) * 128 + 8 * grp), c1 = *(const f32x4*)(cwl + (j * 3 + sec) * 128 + 8 * grp + 4);
;                     y[0] += c0[0] * bflo(w.x); y[1] += c0[1] * bfhi(w.x); y[2] += c0[2] * bflo(w.y); y[3] += c0[3] * bfhi(w.y);
;                     y[4] += c1[0] * bflo(w.z); y[5] += c1[1] * bfhi(w.z); y[6] += c1[2] * bflo(w.w); y[7] += c1[3] * bfhi(w.w); }
; #pragma unroll
;                 for (int e = 0; e < 8; ++e) y[e] = y[e] * __builtin_amdgcn_rcpf(1.f + __expf(-y[e]));
;                 const float gci = gcs[i], bi = bets[i];
;                 if (sec < 2) {
;                     float ss = 0.f;
; #pragma unroll
;                     for (int e = 0; e < 8; ++e) ss += y[e] * y[e];
; #pragma unroll
;                     for (int o = 1; o < 16; o <<= 1) ss += __shfl_xor(ss, o);
;                     const float rn = rsqrtf(ss + RMS_EPS);
;                     if (sec == 0) {
;                         const float sc = rn * 0.08838834764831845f, eg = __expf(gci);
; #pragma unroll
;                         for (int e = 0; e < 8; ++e) y[e] *= sc;
;                         u32x4 w; w.x = cvt_pk_bf16(y[0], y[1]); w.y = cvt_pk_bf16(y[2], y[3]); w.z = cvt_pk_bf16(y[4], y[5]); w.w = cvt_pk_bf16(y[6], y[7]);
;                         *(u32x4*)(qb + i * 136 + 8 * grp) = w;
;                         u32x2 lo, hi; lo.x = cvt_pk_bf16(y[0] * eg, y[1] * eg); lo.y = cvt_pk_bf16(y[2] * eg, y[3] * eg); hi.x = cvt_pk_bf16(y[4] * eg, y[5] * eg); hi.y = cvt_pk_bf16(y[6] * eg, y[7] * eg);
;                         bf16_t* qd = (bf16_t*)(rec + 16384) + i * 128 + 16 * a16;
;                         *(u32x2*)(qd + 4 * bb) = lo; *(u32x2*)(qd + 8 + 4 * bb) = hi;
	v_add_f32_e32 v12, v12, v13
	v_add_f32_e32 v12, 0x358637bd, v12
	v_mul_f32_e32 v13, 0x4b800000, v12
	v_cmp_gt_f32_e32 vcc, s93, v12
	s_nop 1
	v_cndmask_b32_e32 v12, v12, v13, vcc
	v_rsq_f32_e32 v178, v12
	v_add_co_u32_e64 v12, s[20:21], s94, v0
	s_nop 1
	v_addc_co_u32_e64 v13, s[20:21], 0, v1, s[20:21]
	global_store_dwordx2 v[12:13], v[2:3], off
	global_store_dwordx2 v[12:13], v[4:5], off offset:16
	v_mul_f32_e32 v3, 0x3fb8aa3b, v175
	v_mul_f32_e32 v2, 0x45800000, v178
	v_exp_f32_e32 v175, v3
	v_cndmask_b32_e32 v2, v178, v2, vcc
	v_mul_f32_e32 v2, 0x3db504f3, v2
	v_mul_f32_e32 v12, v14, v2
	v_mul_f32_e32 v13, v15, v2
	v_mul_f32_e32 v14, v19, v2
	v_mul_f32_e32 v15, v18, v2
	v_mul_f32_e32 v18, v177, v2
	v_mul_f32_e32 v19, v176, v2
	v_mul_f32_e32 v11, v11, v2
	v_mul_f32_e32 v10, v10, v2
	v_cvt_pk_bf16_f32 v2, v12, v13
	v_cvt_pk_bf16_f32 v3, v14, v15
	v_cvt_pk_bf16_f32 v4, v18, v19
	v_cvt_pk_bf16_f32 v5, v11, v10
	ds_write_b128 v155, v[2:5] offset:8704
	v_mul_f32_e32 v2, v175, v12
	v_mul_f32_e32 v3, v175, v13
	v_cvt_pk_bf16_f32 v2, v2, v3
	v_mul_f32_e32 v3, v175, v14
	v_mul_f32_e32 v4, v175, v15
	v_cvt_pk_bf16_f32 v3, v3, v4
	v_mul_f32_e32 v4, v175, v18
	v_mul_f32_e32 v5, v175, v19
	v_cvt_pk_bf16_f32 v4, v4, v5
	v_mul_f32_e32 v5, v175, v11
	v_mul_f32_e32 v10, v175, v10
	v_cvt_pk_bf16_f32 v5, v5, v10
	ds_read_b128 v[10:13], v17 offset:512
	ds_read_b128 v[176:179], v17 offset:528
	ds_read_b128 v[180:183], v17 offset:2048
	ds_read_b128 v[184:187], v17 offset:2064
	v_lshlrev_b32_e32 v15, 16, v56
	v_lshlrev_b32_e32 v14, 16, v52
	s_waitcnt lgkmcnt(3)
	s_waitcnt lgkmcnt(1)
	v_mul_f32_e32 v14, v10, v14
	v_fma_f32 v15, v180, v15, v14
	v_and_b32_e32 v19, 0xffff0000, v52
	v_and_b32_e32 v18, 0xffff0000, v56
	v_mul_f32_e32 v18, v181, v18
	v_fma_f32 v19, v11, v19, v18
	v_lshlrev_b32_e32 v11, 16, v53
	v_lshlrev_b32_e32 v10, 16, v57
	v_mul_f32_e32 v188, v182, v10
	v_fma_f32 v189, v12, v11, v188
	v_lshlrev_b32_e32 v181, 16, v58
	v_lshlrev_b32_e32 v180, 16, v54
	s_waitcnt lgkmcnt(0)
	v_mul_f32_e32 v192, v176, v180
	v_fma_f32 v193, v184, v181, v192
	v_and_b32_e32 v181, 0xffff0000, v58
	v_and_b32_e32 v180, 0xffff0000, v54
	v_and_b32_e32 v11, 0xffff0000, v53
	v_and_b32_e32 v10, 0xffff0000, v57
	v_mul_f32_e32 v194, v177, v180
	v_fma_f32 v195, v185, v181, v194
	v_lshlrev_b32_e32 v177, 16, v59
	v_lshlrev_b32_e32 v176, 16, v55
	ds_read_b32 v175, v144
	v_mul_f32_e32 v190, v183, v10
	v_fma_f32 v191, v13, v11, v190
	ds_read_b128 v[10:13], v17 offset:3584
	v_mul_f32_e32 v196, v178, v176
	v_fma_f32 v197, v186, v177, v196
	v_and_b32_e32 v177, 0xffff0000, v59
	v_and_b32_e32 v176, 0xffff0000, v55
	v_mul_f32_e32 v198, v179, v176
	v_fma_f32 v199, v187, v177, v198
	ds_read_b128 v[176:179], v17 offset:3600
	ds_read_b128 v[180:183], v17 offset:5120
	ds_read_b128 v[184:187], v17 offset:5136
	s_waitcnt lgkmcnt(3)
	v_add_co_u32_e32 v0, vcc, s95, v0
	s_waitcnt lgkmcnt(1)
	v_fma_f32 v200, v10, v200, v15
	v_fma_f32 v201, v180, v201, v200
	v_and_b32_e32 v203, 0xffff0000, v64
	v_and_b32_e32 v202, 0xffff0000, v60
	v_fma_f32 v10, v11, v202, v19
	v_fma_f32 v11, v181, v203, v10
	v_lshlrev_b32_e32 v181, 16, v65
	v_lshlrev_b32_e32 v180, 16, v61
	v_fma_f32 v180, v12, v180, v189
	v_fma_f32 v181, v182, v181, v180
	v_and_b32_e32 v203, 0xffff0000, v65
	v_and_b32_e32 v202, 0xffff0000, v61
	v_fma_f32 v12, v13, v202, v191
	v_fma_f32 v13, v183, v203, v12
	v_lshlrev_b32_e32 v183, 16, v66
	v_lshlrev_b32_e32 v182, 16, v62
	s_waitcnt lgkmcnt(0)
	v_fma_f32 v182, v176, v182, v193
	v_fma_f32 v183, v184, v183, v182
	v_lshlrev_b32_e32 v203, 16, v67
	v_lshlrev_b32_e32 v202, 16, v63
	v_fma_f32 v202, v178, v202, v197
	v_fma_f32 v203, v186, v203, v202
	v_and_b32_e32 v205, 0xffff0000, v67
	v_and_b32_e32 v204, 0xffff0000, v63
	v_fma_f32 v178, v179, v204, v199
	v_fma_f32 v178, v187, v205, v178
	v_and_b32_e32 v187, 0xffff0000, v66
	v_mul_f32_e32 v176, 0xbfb8aa3b, v203
	v_exp_f32_e32 v176, v176
	v_mul_f32_e32 v184, 0xbfb8aa3b, v178
	v_exp_f32_e32 v184, v184
	v_and_b32_e32 v186, 0xffff0000, v62
	v_add_f32_e32 v176, 1.0, v176
	v_rcp_f32_e32 v197, v176
	v_add_f32_e32 v176, 1.0, v184
	v_rcp_f32_e32 v196, v176
	v_fma_f32 v176, v177, v186, v195
	v_fma_f32 v177, v185, v187, v176
	v_mul_f32_e32 v182, 0xbfb8aa3b, v183
	v_exp_f32_e32 v184, v182
	v_mul_f32_e32 v182, 0xbfb8aa3b, v177
	v_exp_f32_e32 v185, v182
	v_add_f32_e32 v184, 1.0, v184
	v_add_f32_e32 v185, 1.0, v185
	v_rcp_f32_e32 v184, v184
	v_rcp_f32_e32 v185, v185
	v_mul_f32_e32 v178, v178, v196
	v_mul_f32_e32 v179, v203, v197
	v_mul_f32_e32 v14, 0xbfb8aa3b, v201
	v_exp_f32_e32 v18, v14
	v_mul_f32_e32 v14, 0xbfb8aa3b, v11
	v_exp_f32_e32 v19, v14
	v_mul_f32_e32 v14, v183, v184
	v_mul_f32_e32 v15, v177, v185
	v_mov_b32_e32 v12, v181
	v_add_f32_e32 v18, 1.0, v18
	v_mul_f32_e32 v176, 0xbfb8aa3b, v181
	v_mul_f32_e32 v177, 0xbfb8aa3b, v13
	v_exp_f32_e32 v176, v176
	v_exp_f32_e32 v177, v177
	v_add_f32_e32 v19, 1.0, v19
	v_rcp_f32_e32 v18, v18
	v_rcp_f32_e32 v19, v19
	v_add_f32_e32 v176, 1.0, v176
	v_add_f32_e32 v177, 1.0, v177
	v_rcp_f32_e32 v176, v176
	v_rcp_f32_e32 v177, v177
	v_mul_f32_e32 v10, v201, v18
	v_mul_f32_e32 v11, v11, v19
	v_mul_f32_e32 v180, v14, v14
	v_mul_f32_e32 v181, v15, v15
	v_mul_f32_e32 v18, v10, v10
	v_mul_f32_e32 v19, v11, v11
	v_mul_f32_e32 v12, v12, v176
	v_mul_f32_e32 v13, v13, v177
	v_add_f32_e32 v18, v18, v19
	v_mul_f32_e32 v176, v12, v12
	v_mul_f32_e32 v177, v13, v13
	v_mul_f32_e32 v182, v178, v178
	v_mul_f32_e32 v183, v179, v179
	v_add_f32_e32 v18, v176, v18
	v_add_f32_e32 v18, v177, v18
	v_add_f32_e32 v18, v180, v18
	v_add_f32_e32 v18, v181, v18
	v_add_f32_e32 v18, v183, v18
	v_add_f32_e32 v18, v182, v18
	ds_bpermute_b32 v19, v6, v18
	v_addc_co_u32_e32 v1, vcc, 0, v1, vcc
	ds_read_b32 v176, v143
	global_store_dwordx2 v[0:1], v[2:3], off
	global_store_dwordx2 v[0:1], v[4:5], off offset:16
	s_waitcnt lgkmcnt(1)
; __device__ __forceinline__ void gdn_prep_item(const Params& p, unsigned char* lds, int item, u32x4 (&raw)[3][2][4], float& gpre, float& bpre, int next_item) {
;     ...
;                 for (int j = 0; j < 4; ++j) { const u32x4 w = raw[sec][ps][j];
;                     const f32x4 c0 = *(const f32x4*)(cwl + (j * 3 + sec) * 128 + 8 * grp), c1 = *(const f32x4*)(cwl + (j * 3 + sec) * 128 + 8 * grp + 4);
;                     y[0] += c0[0] * bflo(w.x); y[1] += c0[1] * bfhi(w.x); y[2] += c0[2] * bflo(w.y); y[3] += c0[3] * bfhi(w.y);
;                     y[4] += c1[0] * bflo(w.z); y[5] += c1[1] * bfhi(w.z); y[6] += c1[2] * bflo(w.w); y[7] += c1[3] * bfhi(w.w); }
; #pragma unroll
;                 for (int e = 0; e < 8; ++e) y[e] = y[e] * __builtin_amdgcn_rcpf(1.f + __expf(-y[e]));
;                 const float gci = gcs[i], bi = bets[i];
;                 if (sec < 2) {
;                     float ss = 0.f;
; #pragma unroll
;                     for (int e = 0; e < 8; ++e) ss += y[e] * y[e];
; #pragma unroll
;                     for (int o = 1; o < 16; o <<= 1) ss += __shfl_xor(ss, o);
;                     const float rn = rsqrtf(ss + RMS_EPS);
;                     if (sec == 0) {
;                         const float sc = rn * 0.08838834764831845f, eg = __expf(gci);
; #pragma unroll
;                         for (int e = 0; e < 8; ++e) y[e] *= sc;
;                         u32x4 w; w.x = cvt_pk_bf16(y[0], y[1]); w.y = cvt_pk_bf16(y[2], y[3]); w.z = cvt_pk_bf16(y[4], y[5]); w.w = cvt_pk_bf16(y[6], y[7]);
;                         *(u32x4*)(qb + i * 136 + 8 * grp) = w;
;                         u32x2 lo, hi; lo.x = cvt_pk_bf16(y[0] * eg, y[1] * eg); lo.y = cvt_pk_bf16(y[2] * eg, y[3] * eg); hi.x = cvt_pk_bf16(y[4] * eg, y[5] * eg); hi.y = cvt_pk_bf16(y[6] * eg, y[7] * eg);
;                         bf16_t* qd = (bf16_t*)(rec + 16384) + i * 128 + 16 * a16;
;                         *(u32x2*)(qd + 4 * bb) = lo; *(u32x2*)(qd + 8 + 4 * bb) = hi;
;                     } else {
; #pragma unroll
;                         for (int e = 0; e < 8; ++e) y[e] *= rn;
;                         u32x4 w; w.x = cvt_pk_bf16(y[0], y[1]); w.y = cvt_pk_bf16(y[2], y[3]); w.z = cvt_pk_bf16(y[4], y[5]); w.w = cvt_pk_bf16(y[6], y[7]);
;                         *(u32x4*)(kb + i * 136 + 8 * grp) = w;
;                         const float f1 = bi * __expf(gci), f2 = __expf(glast - gci);
	v_add_f32_e32 v18, v18, v19
	ds_bpermute_b32 v19, v7, v18
	s_waitcnt vmcnt(9)
	v_lshlrev_b32_e32 v195, 16, v80
	s_waitcnt lgkmcnt(1)
	v_mul_f32_e32 v177, 0x3fb8aa3b, v176
	v_exp_f32_e32 v177, v177
	v_lshlrev_b32_e32 v194, 16, v76
	s_waitcnt lgkmcnt(0)
	v_add_f32_e32 v18, v18, v19
	ds_bpermute_b32 v19, v8, v18
	v_mul_f32_e32 v4, v175, v177
	v_lshlrev_b32_e32 v200, 16, v85
	v_and_b32_e32 v201, 0xffff0000, v85
	v_lshlrev_b32_e32 v202, 16, v86
	s_waitcnt lgkmcnt(0)
	v_add_f32_e32 v18, v18, v19
	ds_bpermute_b32 v19, v9, v18
	v_and_b32_e32 v203, 0xffff0000, v86
	v_lshlrev_b32_e32 v204, 16, v87
	v_and_b32_e32 v205, 0xffff0000, v87
	s_waitcnt lgkmcnt(0)
	v_add_f32_e32 v0, v18, v19
	v_add_f32_e32 v0, 0x358637bd, v0
	v_mul_f32_e32 v1, 0x4b800000, v0
	v_cmp_gt_f32_e32 vcc, s93, v0
	s_nop 1
	v_cndmask_b32_e32 v0, v0, v1, vcc
	v_rsq_f32_e32 v0, v0
	v_sub_f32_e32 v1, v174, v176
	v_mul_f32_e32 v1, 0x3fb8aa3b, v1
	v_exp_f32_e32 v5, v1
	v_mul_f32_e32 v1, 0x45800000, v0
	v_cndmask_b32_e32 v18, v0, v1, vcc
	v_mul_f32_e32 v180, v10, v18
	v_mul_f32_e32 v181, v11, v18
	v_mul_f32_e32 v182, v12, v18
	v_mul_f32_e32 v183, v13, v18
	v_mul_f32_e32 v14, v14, v18
	v_mul_f32_e32 v15, v15, v18
	v_cvt_pk_bf16_f32 v0, v180, v181
	v_cvt_pk_bf16_f32 v1, v182, v183
	v_mul_f32_e32 v19, v179, v18
	v_mul_f32_e32 v18, v178, v18
	v_cvt_pk_bf16_f32 v2, v14, v15
	v_mul_f32_e32 v12, v4, v182
	v_mul_f32_e32 v13, v4, v183
	v_cvt_pk_bf16_f32 v3, v19, v18
	ds_write_b128 v155, v[0:3] offset:17408
	v_mul_f32_e32 v0, v4, v18
	v_mul_f32_e32 v1, v4, v19
	v_mov_b32_e32 v179, v0
	v_mul_f32_e32 v0, v5, v180
	v_mov_b32_e32 v178, v1
	v_bfe_u32 v1, v0, 16, 1
	v_mul_f32_e32 v10, v4, v180
	v_mul_f32_e32 v11, v4, v181
	v_mul_f32_e32 v176, v4, v14
	v_mul_f32_e32 v177, v4, v15
	v_add3_u32 v0, v0, v1, s96
	ds_write_b128 v161, v[10:13] offset:34816
	ds_write_b128 v161, v[176:179] offset:34832
	ds_write_b16_d16_hi v159, v0
	v_mul_f32_e32 v0, v5, v181
	v_bfe_u32 v1, v0, 16, 1
	v_add3_u32 v0, v0, v1, s96
	ds_write_b16_d16_hi v159, v0 offset:144
	v_mul_f32_e32 v0, v5, v182
	v_bfe_u32 v1, v0, 16, 1
	v_add3_u32 v0, v0, v1, s96
	ds_write_b16_d16_hi v159, v0 offset:288
	v_mul_f32_e32 v0, v5, v183
	v_bfe_u32 v1, v0, 16, 1
	v_add3_u32 v0, v0, v1, s96
	ds_write_b16_d16_hi v159, v0 offset:432
	v_mul_f32_e32 v0, v5, v14
	v_bfe_u32 v1, v0, 16, 1
	v_add3_u32 v0, v0, v1, s96
	ds_write_b16_d16_hi v159, v0 offset:576
	v_mul_f32_e32 v0, v5, v15
	v_bfe_u32 v1, v0, 16, 1
	v_add3_u32 v0, v0, v1, s96
	ds_write_b16_d16_hi v159, v0 offset:720
	v_mul_f32_e32 v0, v5, v19
	v_bfe_u32 v1, v0, 16, 1
	v_add3_u32 v0, v0, v1, s96
	ds_write_b16_d16_hi v159, v0 offset:864
	v_mul_f32_e32 v0, v5, v18
	v_bfe_u32 v1, v0, 16, 1
	v_add3_u32 v0, v0, v1, s96
	ds_write_b16_d16_hi v159, v0 offset:1008
	ds_read_b128 v[0:3], v17 offset:512
	ds_read_b128 v[10:13], v17 offset:528
	ds_read_b128 v[176:179], v17 offset:2048
	ds_read_b128 v[180:183], v17 offset:2064
	v_lshlrev_b32_e32 v5, 16, v72
	v_lshlrev_b32_e32 v4, 16, v68
	s_waitcnt lgkmcnt(3)
	s_waitcnt lgkmcnt(1)
	v_mul_f32_e32 v4, v0, v4
	v_fma_f32 v5, v176, v5, v4
	v_and_b32_e32 v15, 0xffff0000, v68
	v_and_b32_e32 v14, 0xffff0000, v72
	v_mov_b32_e32 v0, v177
	v_lshlrev_b32_e32 v177, 16, v74
	v_lshlrev_b32_e32 v176, 16, v70
	s_waitcnt lgkmcnt(0)
	v_mul_f32_e32 v14, v0, v14
	v_fma_f32 v15, v1, v15, v14
	v_lshlrev_b32_e32 v1, 16, v69
	v_lshlrev_b32_e32 v0, 16, v73
	v_mul_f32_e32 v186, v10, v176
	v_fma_f32 v187, v180, v177, v186
	v_and_b32_e32 v177, 0xffff0000, v74
	v_and_b32_e32 v176, 0xffff0000, v70
	v_mul_f32_e32 v18, v178, v0
	v_fma_f32 v19, v2, v1, v18
	v_and_b32_e32 v1, 0xffff0000, v69
	v_and_b32_e32 v0, 0xffff0000, v73
	v_mul_f32_e32 v188, v11, v176
	v_fma_f32 v189, v181, v177, v188
	v_lshlrev_b32_e32 v11, 16, v75
	v_lshlrev_b32_e32 v10, 16, v71
	ds_read_b32 v175, v146
	v_mul_f32_e32 v184, v179, v0
	v_fma_f32 v185, v3, v1, v184
	ds_read_b128 v[0:3], v17 offset:3584
	v_mul_f32_e32 v190, v12, v10
	v_fma_f32 v191, v182, v11, v190
	v_and_b32_e32 v11, 0xffff0000, v75
	v_and_b32_e32 v10, 0xffff0000, v71
	v_mul_f32_e32 v192, v13, v10
	v_fma_f32 v193, v183, v11, v192
	ds_read_b128 v[10:13], v17 offset:3600
	ds_read_b128 v[176:179], v17 offset:5120
	ds_read_b128 v[180:183], v17 offset:5136
	s_waitcnt lgkmcnt(3)
	s_waitcnt lgkmcnt(2)
	s_waitcnt lgkmcnt(1)
	v_fma_f32 v194, v0, v194, v5
	v_fma_f32 v195, v176, v195, v194
	v_and_b32_e32 v197, 0xffff0000, v80
	v_and_b32_e32 v196, 0xffff0000, v76
	v_fma_f32 v0, v1, v196, v15
	v_fma_f32 v1, v177, v197, v0
	v_lshlrev_b32_e32 v177, 16, v81
	v_lshlrev_b32_e32 v176, 16, v77
	v_fma_f32 v176, v2, v176, v19
	v_fma_f32 v177, v178, v177, v176
	v_and_b32_e32 v197, 0xffff0000, v81
	v_and_b32_e32 v196, 0xffff0000, v77
	v_fma_f32 v2, v3, v196, v185
	v_fma_f32 v3, v179, v197, v2
	v_lshlrev_b32_e32 v179, 16, v82
	v_lshlrev_b32_e32 v178, 16, v78
	s_waitcnt lgkmcnt(0)
; __device__ __forceinline__ void gdn_prep_item(const Params& p, unsigned char* lds, int item, u32x4 (&raw)[3][2][4], float& gpre, float& bpre, int next_item) {
;     ...
;                 for (int j = 0; j < 4; ++j) { const u32x4 w = raw[sec][ps][j];
;                     const f32x4 c0 = *(const f32x4*)(cwl + (j * 3 + sec) * 128 + 8 * grp), c1 = *(const f32x4*)(cwl + (j * 3 + sec) * 128 + 8 * grp + 4);
;                     y[0] += c0[0] * bflo(w.x); y[1] += c0[1] * bfhi(w.x); y[2] += c0[2] * bflo(w.y); y[3] += c0[3] * bfhi(w.y);
;                     y[4] += c1[0] * bflo(w.z); y[5] += c1[1] * bfhi(w.z); y[6] += c1[2] * bflo(w.w); y[7] += c1[3] * bfhi(w.w); }
; #pragma unroll
;                 for (int e = 0; e < 8; ++e) y[e] = y[e] * __builtin_amdgcn_rcpf(1.f + __expf(-y[e]));
;                 const float gci = gcs[i], bi = bets[i];
;                 if (sec < 2) {
;                     float ss = 0.f;
; #pragma unroll
;                     for (int e = 0; e < 8; ++e) ss += y[e] * y[e];
; #pragma unroll
;                     for (int o = 1; o < 16; o <<= 1) ss += __shfl_xor(ss, o);
;                     const float rn = rsqrtf(ss + RMS_EPS);
;                     if (sec == 0) {
;                         const float sc = rn * 0.08838834764831845f, eg = __expf(gci);
; #pragma unroll
;                         for (int e = 0; e < 8; ++e) y[e] *= sc;
;                         u32x4 w; w.x = cvt_pk_bf16(y[0], y[1]); w.y = cvt_pk_bf16(y[2], y[3]); w.z = cvt_pk_bf16(y[4], y[5]); w.w = cvt_pk_bf16(y[6], y[7]);
;                         *(u32x4*)(qb + i * 136 + 8 * grp) = w;
;                         u32x2 lo, hi; lo.x = cvt_pk_bf16(y[0] * eg, y[1] * eg); lo.y = cvt_pk_bf16(y[2] * eg, y[3] * eg); hi.x = cvt_pk_bf16(y[4] * eg, y[5] * eg); hi.y = cvt_pk_bf16(y[6] * eg, y[7] * eg);
;                         bf16_t* qd = (bf16_t*)(rec + 16384) + i * 128 + 16 * a16;
;                         *(u32x2*)(qd + 4 * bb) = lo; *(u32x2*)(qd + 8 + 4 * bb) = hi;
;                     } else {
; #pragma unroll
;                         for (int e = 0; e < 8; ++e) y[e] *= rn;
;                         u32x4 w; w.x = cvt_pk_bf16(y[0], y[1]); w.y = cvt_pk_bf16(y[2], y[3]); w.z = cvt_pk_bf16(y[4], y[5]); w.w = cvt_pk_bf16(y[6], y[7]);
;                         *(u32x4*)(kb + i * 136 + 8 * grp) = w;
;                         const float f1 = bi * __expf(gci), f2 = __expf(glast - gci);
	v_fma_f32 v178, v10, v178, v187
	v_fma_f32 v179, v180, v179, v178
	v_lshlrev_b32_e32 v197, 16, v83
	v_lshlrev_b32_e32 v196, 16, v79
	v_fma_f32 v196, v12, v196, v191
	v_fma_f32 v197, v182, v197, v196
	v_and_b32_e32 v199, 0xffff0000, v83
	v_and_b32_e32 v198, 0xffff0000, v79
	v_fma_f32 v12, v13, v198, v193
	v_fma_f32 v12, v183, v199, v12
	v_and_b32_e32 v183, 0xffff0000, v82
	v_mul_f32_e32 v10, 0xbfb8aa3b, v197
	v_exp_f32_e32 v10, v10
	v_mul_f32_e32 v180, 0xbfb8aa3b, v12
	v_exp_f32_e32 v180, v180
	v_and_b32_e32 v182, 0xffff0000, v78
	v_add_f32_e32 v10, 1.0, v10
	v_rcp_f32_e32 v191, v10
	v_add_f32_e32 v10, 1.0, v180
	v_rcp_f32_e32 v190, v10
	v_fma_f32 v10, v11, v182, v189
	v_fma_f32 v11, v181, v183, v10
	v_mul_f32_e32 v178, 0xbfb8aa3b, v179
	v_exp_f32_e32 v180, v178
	v_mul_f32_e32 v178, 0xbfb8aa3b, v11
	v_exp_f32_e32 v181, v178
	v_add_f32_e32 v180, 1.0, v180
	v_mul_f32_e32 v4, 0xbfb8aa3b, v195
	v_add_f32_e32 v181, 1.0, v181
	v_exp_f32_e32 v14, v4
	v_mul_f32_e32 v4, 0xbfb8aa3b, v1
	v_rcp_f32_e32 v180, v180
	v_rcp_f32_e32 v181, v181
	v_exp_f32_e32 v15, v4
	v_mul_f32_e32 v12, v12, v190
	v_mul_f32_e32 v13, v197, v191
	v_lshlrev_b32_e32 v198, 16, v89
	v_mul_f32_e32 v4, v179, v180
	v_mul_f32_e32 v5, v11, v181
	v_add_f32_e32 v10, 1.0, v14
	v_add_f32_e32 v11, 1.0, v15
	v_rcp_f32_e32 v10, v10
	v_mul_f32_e32 v14, 0xbfb8aa3b, v177
	v_mul_f32_e32 v15, 0xbfb8aa3b, v3
	v_exp_f32_e32 v14, v14
	v_exp_f32_e32 v15, v15
	v_rcp_f32_e32 v11, v11
	v_mul_f32_e32 v18, v4, v4
	v_mul_f32_e32 v19, v5, v5
	v_add_f32_e32 v14, 1.0, v14
	v_add_f32_e32 v15, 1.0, v15
	v_rcp_f32_e32 v14, v14
	v_rcp_f32_e32 v15, v15
	v_mul_f32_e32 v0, v195, v10
	v_mul_f32_e32 v1, v1, v11
	v_mul_f32_e32 v178, v12, v12
	v_mul_f32_e32 v179, v13, v13
	v_mul_f32_e32 v10, v0, v0
	v_mul_f32_e32 v11, v1, v1
	v_mul_f32_e32 v2, v177, v14
	v_mul_f32_e32 v3, v3, v15
	v_add_f32_e32 v10, v10, v11
	v_mul_f32_e32 v14, v2, v2
	v_mul_f32_e32 v15, v3, v3
	ds_read_b32 v11, v145
	v_add_f32_e32 v10, v14, v10
	v_add_f32_e32 v10, v15, v10
	v_add_f32_e32 v10, v18, v10
	v_add_f32_e32 v10, v19, v10
	v_add_f32_e32 v10, v179, v10
	v_add_f32_e32 v10, v178, v10
	ds_bpermute_b32 v6, v6, v10
	v_and_b32_e32 v199, 0xffff0000, v89
	v_lshlrev_b32_e32 v196, 16, v93
	v_and_b32_e32 v197, 0xffff0000, v93
	s_waitcnt vmcnt(8)
	v_lshlrev_b32_e32 v194, 16, v97
	s_waitcnt lgkmcnt(0)
	v_add_f32_e32 v6, v10, v6
	ds_bpermute_b32 v7, v7, v6
	v_and_b32_e32 v195, 0xffff0000, v97
	s_waitcnt lgkmcnt(0)
	v_add_f32_e32 v6, v6, v7
	ds_bpermute_b32 v7, v8, v6
	v_mul_f32_e32 v8, 0x3fb8aa3b, v11
	v_exp_f32_e32 v8, v8
	s_waitcnt lgkmcnt(0)
	v_add_f32_e32 v6, v6, v7
	ds_bpermute_b32 v7, v9, v6
	v_mul_f32_e32 v10, v175, v8
	s_waitcnt lgkmcnt(0)
	v_add_f32_e32 v6, v6, v7
	v_add_f32_e32 v6, 0x358637bd, v6
	v_mul_f32_e32 v7, 0x4b800000, v6
	v_cmp_gt_f32_e32 vcc, s93, v6
	s_nop 1
	v_cndmask_b32_e32 v6, v6, v7, vcc
	v_rsq_f32_e32 v6, v6
	v_sub_f32_e32 v7, v174, v11
	v_mul_f32_e32 v7, 0x3fb8aa3b, v7
	v_exp_f32_e32 v15, v7
	v_mul_f32_e32 v7, 0x45800000, v6
	v_cndmask_b32_e32 v14, v6, v7, vcc
	v_mul_f32_e32 v18, v0, v14
	v_mul_f32_e32 v19, v1, v14
	v_mul_f32_e32 v174, v2, v14
	v_mul_f32_e32 v175, v3, v14
	v_cvt_pk_bf16_f32 v0, v18, v19
	v_mul_f32_e32 v12, v12, v14
	v_mul_f32_e32 v13, v13, v14
	v_cvt_pk_bf16_f32 v1, v174, v175
	v_mul_f32_e32 v176, v4, v14
	v_mul_f32_e32 v177, v5, v14
	v_mul_f32_e32 v6, v10, v174
	v_mul_f32_e32 v7, v10, v175
	v_cvt_pk_bf16_f32 v2, v176, v177
	v_cvt_pk_bf16_f32 v3, v13, v12
	ds_write_b128 v155, v[0:3] offset:26112
	v_mul_f32_e32 v0, v10, v12
	v_mul_f32_e32 v1, v10, v13
	v_mul_f32_e32 v4, v10, v18
	v_mul_f32_e32 v5, v10, v19
	v_mul_f32_e32 v8, v10, v176
	v_mul_f32_e32 v9, v10, v177
	v_mov_b32_e32 v11, v0
	v_mul_f32_e32 v0, v15, v18
	v_mov_b32_e32 v10, v1
	v_bfe_u32 v1, v0, 16, 1
	v_add3_u32 v0, v0, v1, s96
	ds_write_b128 v161, v[4:7] offset:51712
	ds_write_b128 v161, v[8:11] offset:51728
	ds_write_b16_d16_hi v160, v0
	v_mul_f32_e32 v0, v15, v19
	v_bfe_u32 v1, v0, 16, 1
	v_add3_u32 v0, v0, v1, s96
	ds_write_b16_d16_hi v160, v0 offset:144
	v_mul_f32_e32 v0, v15, v174
	v_bfe_u32 v1, v0, 16, 1
	v_add3_u32 v0, v0, v1, s96
	ds_write_b16_d16_hi v160, v0 offset:288
	v_mul_f32_e32 v0, v15, v175
	v_bfe_u32 v1, v0, 16, 1
	v_add3_u32 v0, v0, v1, s96
	ds_write_b16_d16_hi v160, v0 offset:432
	v_mul_f32_e32 v0, v15, v176
	v_bfe_u32 v1, v0, 16, 1
	v_add3_u32 v0, v0, v1, s96
	ds_write_b16_d16_hi v160, v0 offset:576
	v_mul_f32_e32 v0, v15, v177
	v_bfe_u32 v1, v0, 16, 1
	v_add3_u32 v0, v0, v1, s96
	ds_write_b16_d16_hi v160, v0 offset:720
	v_mul_f32_e32 v0, v15, v13
	v_bfe_u32 v1, v0, 16, 1
	v_add3_u32 v0, v0, v1, s96
	ds_write_b16_d16_hi v160, v0 offset:864
	v_mul_f32_e32 v0, v15, v12
	v_bfe_u32 v1, v0, 16, 1
	v_add3_u32 v0, v0, v1, s96
	ds_write_b16_d16_hi v160, v0 offset:1008
	ds_read_b32 v18, v144
	ds_read_b128 v[174:177], v17 offset:1024
	ds_read_b128 v[0:3], v17 offset:4112
	ds_read_b128 v[178:181], v17 offset:5632
	ds_read_b128 v[4:7], v17 offset:2576
	ds_read_b128 v[182:185], v17 offset:4096
	ds_read_b128 v[8:11], v17 offset:1040
	ds_read_b128 v[186:189], v17 offset:2560
	v_lshlrev_b32_e32 v12, 16, v84
	v_and_b32_e32 v13, 0xffff0000, v84
	s_waitcnt lgkmcnt(6)
	v_fma_f32 v12, v174, v12, 0
	v_fma_f32 v13, v175, v13, 0
	v_lshlrev_b32_e32 v14, 16, v88
	v_and_b32_e32 v15, 0xffff0000, v88
	s_waitcnt lgkmcnt(0)
; __device__ __forceinline__ float bflo(unsigned w) { return __uint_as_float(w << 16); }
; __device__ __forceinline__ float bfhi(unsigned w) { return __uint_as_float(w & 0xffff0000u); }
; #define LBAR() asm volatile("s_waitcnt lgkmcnt(0)\n\ts_barrier" ::: "memory")
; __device__ __forceinline__ void gdn_prep_item(const Params& p, unsigned char* lds, int item, u32x4 (&raw)[3][2][4], float& gpre, float& bpre, int next_item) {
;     ...
;                 for (int j = 0; j < 4; ++j) { const u32x4 w = raw[sec][ps][j];
;                     const f32x4 c0 = *(const f32x4*)(cwl + (j * 3 + sec) * 128 + 8 * grp), c1 = *(const f32x4*)(cwl + (j * 3 + sec) * 128 + 8 * grp + 4);
;                     y[0] += c0[0] * bflo(w.x); y[1] += c0[1] * bfhi(w.x); y[2] += c0[2] * bflo(w.y); y[3] += c0[3] * bfhi(w.y);
;                     y[4] += c1[0] * bflo(w.z); y[5] += c1[1] * bfhi(w.z); y[6] += c1[2] * bflo(w.w); y[7] += c1[3] * bfhi(w.w); }
; #pragma unroll
;                 for (int e = 0; e < 8; ++e) y[e] = y[e] * __builtin_amdgcn_rcpf(1.f + __expf(-y[e]));
;     ...
;                 } else {
;                     f32x4 r0 = {y[0] * bi, y[1] * bi, y[2] * bi, y[3] * bi}, r1 = {y[4] * bi, y[5] * bi, y[6] * bi, y[7] * bi};
;                     *(f32x4*)(rhsV + i * RS + 8 * grp) = r0; *(f32x4*)(rhsV + i * RS + 8 * grp + 4) = r1;
;                 }
;             }
;         }
;     }
;     LBAR();
	v_fma_f32 v12, v186, v14, v12
	v_fma_f32 v13, v187, v15, v13
	v_lshlrev_b32_e32 v14, 16, v92
	v_and_b32_e32 v15, 0xffff0000, v92
	v_fma_f32 v12, v182, v14, v12
	v_fma_f32 v13, v183, v15, v13
	v_lshlrev_b32_e32 v14, 16, v96
	v_and_b32_e32 v15, 0xffff0000, v96
	v_fma_f32 v190, v178, v14, v12
	v_fma_f32 v191, v179, v15, v13
	v_fma_f32 v200, v176, v200, 0
	v_fma_f32 v201, v177, v201, 0
	v_mul_f32_e32 v12, 0xbfb8aa3b, v191
	v_exp_f32_e32 v19, v12
	v_mul_f32_e32 v12, 0xbfb8aa3b, v190
	v_exp_f32_e32 v192, v12
	v_fma_f32 v198, v188, v198, v200
	v_fma_f32 v199, v189, v199, v201
	ds_read_b128 v[12:15], v17 offset:5648
	v_fma_f32 v196, v184, v196, v198
	v_fma_f32 v197, v185, v197, v199
	v_add_f32_e32 v17, 1.0, v19
	v_fma_f32 v194, v180, v194, v196
	v_fma_f32 v195, v181, v195, v197
	v_rcp_f32_e32 v193, v17
	v_add_f32_e32 v17, 1.0, v192
	v_mul_f32_e32 v19, 0xbfb8aa3b, v195
	v_mul_f32_e32 v192, 0xbfb8aa3b, v194
	v_exp_f32_e32 v19, v19
	v_exp_f32_e32 v196, v192
	v_rcp_f32_e32 v192, v17
	v_lshlrev_b32_e32 v200, 16, v90
	v_and_b32_e32 v201, 0xffff0000, v90
	v_fma_f32 v202, v8, v202, 0
	v_fma_f32 v203, v9, v203, 0
	v_lshlrev_b32_e32 v198, 16, v94
	v_and_b32_e32 v199, 0xffff0000, v94
	v_fma_f32 v200, v4, v200, v202
	v_fma_f32 v201, v5, v201, v203
	v_add_f32_e32 v17, 1.0, v19
	v_mul_f32_e32 v190, v190, v192
	v_mul_f32_e32 v191, v191, v193
	v_lshlrev_b32_e32 v192, 16, v98
	v_and_b32_e32 v193, 0xffff0000, v98
	v_fma_f32 v198, v0, v198, v200
	v_fma_f32 v199, v1, v199, v201
	v_rcp_f32_e32 v197, v17
	v_add_f32_e32 v17, 1.0, v196
	s_waitcnt lgkmcnt(0)
	v_fma_f32 v198, v12, v192, v198
	v_fma_f32 v199, v13, v193, v199
	v_rcp_f32_e32 v196, v17
	v_mul_f32_e32 v17, 0xbfb8aa3b, v199
	v_exp_f32_e32 v17, v17
	v_mul_f32_e32 v19, 0xbfb8aa3b, v198
	v_exp_f32_e32 v19, v19
	v_lshlrev_b32_e32 v202, 16, v91
	v_and_b32_e32 v203, 0xffff0000, v91
	v_fma_f32 v204, v10, v204, 0
	v_fma_f32 v205, v11, v205, 0
	v_lshlrev_b32_e32 v200, 16, v95
	v_and_b32_e32 v201, 0xffff0000, v95
	v_fma_f32 v202, v6, v202, v204
	v_fma_f32 v203, v7, v203, v205
	v_mul_f32_e32 v192, v194, v196
	v_mul_f32_e32 v193, v195, v197
	v_lshlrev_b32_e32 v196, 16, v99
	v_and_b32_e32 v197, 0xffff0000, v99
	v_fma_f32 v200, v2, v200, v202
	v_fma_f32 v201, v3, v201, v203
	v_add_f32_e32 v17, 1.0, v17
	v_fma_f32 v196, v14, v196, v200
	v_fma_f32 v197, v15, v197, v201
	v_rcp_f32_e32 v195, v17
	v_add_f32_e32 v17, 1.0, v19
	v_mul_f32_e32 v19, 0xbfb8aa3b, v197
	v_exp_f32_e32 v19, v19
	v_mul_f32_e32 v194, 0xbfb8aa3b, v196
	v_exp_f32_e32 v200, v194
	v_rcp_f32_e32 v194, v17
	v_add_f32_e32 v17, 1.0, v19
	v_rcp_f32_e32 v201, v17
	v_add_f32_e32 v17, 1.0, v200
	v_rcp_f32_e32 v200, v17
	v_mul_f32_e32 v194, v198, v194
	v_mul_f32_e32 v195, v199, v195
	v_mul_f32_e32 v192, v18, v192
	v_mul_f32_e32 v193, v18, v193
	v_mul_f32_e32 v190, v18, v190
	v_mul_f32_e32 v191, v18, v191
	v_mul_f32_e32 v196, v196, v200
	v_mul_f32_e32 v197, v197, v201
	v_mul_f32_e32 v194, v18, v194
	v_mul_f32_e32 v195, v18, v195
	v_mul_f32_e32 v196, v18, v196
	v_mul_f32_e32 v197, v18, v197
	s_waitcnt vmcnt(7)
	v_lshlrev_b32_e32 v18, 16, v100
	v_and_b32_e32 v19, 0xffff0000, v100
	v_fma_f32 v18, v174, v18, 0
	v_fma_f32 v19, v175, v19, 0
	s_waitcnt vmcnt(6)
	v_lshlrev_b32_e32 v174, 16, v104
	v_and_b32_e32 v175, 0xffff0000, v104
	v_fma_f32 v18, v186, v174, v18
	v_fma_f32 v19, v187, v175, v19
	s_waitcnt vmcnt(5)
	v_lshlrev_b32_e32 v174, 16, v108
	v_and_b32_e32 v175, 0xffff0000, v108
	v_fma_f32 v18, v182, v174, v18
	v_fma_f32 v19, v183, v175, v19
	s_waitcnt vmcnt(4)
	v_lshlrev_b32_e32 v174, 16, v112
	v_and_b32_e32 v175, 0xffff0000, v112
	v_fma_f32 v18, v178, v174, v18
	v_fma_f32 v19, v179, v175, v19
	ds_write_b128 v162, v[190:193]
	ds_write_b128 v162, v[194:197] offset:16
	v_mul_f32_e32 v17, 0xbfb8aa3b, v19
	v_exp_f32_e32 v17, v17
	v_mul_f32_e32 v174, 0xbfb8aa3b, v18
	v_lshlrev_b32_e32 v192, 16, v101
	v_and_b32_e32 v193, 0xffff0000, v101
	v_exp_f32_e32 v175, v174
	v_lshlrev_b32_e32 v190, 16, v105
	v_and_b32_e32 v191, 0xffff0000, v105
	v_fma_f32 v176, v176, v192, 0
	v_fma_f32 v177, v177, v193, 0
	v_lshlrev_b32_e32 v186, 16, v109
	v_and_b32_e32 v187, 0xffff0000, v109
	v_fma_f32 v176, v188, v190, v176
	v_fma_f32 v177, v189, v191, v177
	v_lshlrev_b32_e32 v182, 16, v113
	v_and_b32_e32 v183, 0xffff0000, v113
	v_fma_f32 v176, v184, v186, v176
	v_fma_f32 v177, v185, v187, v177
	v_add_f32_e32 v17, 1.0, v17
	v_fma_f32 v176, v180, v182, v176
	v_fma_f32 v177, v181, v183, v177
	v_rcp_f32_e32 v179, v17
	v_add_f32_e32 v17, 1.0, v175
	v_mul_f32_e32 v175, 0xbfb8aa3b, v177
	v_exp_f32_e32 v175, v175
	v_mul_f32_e32 v178, 0xbfb8aa3b, v176
	v_exp_f32_e32 v180, v178
	v_rcp_f32_e32 v178, v17
	v_lshlrev_b32_e32 v186, 16, v102
	v_and_b32_e32 v187, 0xffff0000, v102
	v_lshlrev_b32_e32 v184, 16, v106
	v_and_b32_e32 v185, 0xffff0000, v106
	v_fma_f32 v8, v8, v186, 0
	v_fma_f32 v9, v9, v187, 0
	v_add_f32_e32 v17, 1.0, v175
	v_lshlrev_b32_e32 v182, 16, v110
	v_and_b32_e32 v183, 0xffff0000, v110
	v_fma_f32 v4, v4, v184, v8
	v_fma_f32 v5, v5, v185, v9
	v_rcp_f32_e32 v181, v17
	v_add_f32_e32 v17, 1.0, v180
	v_mul_f32_e32 v18, v18, v178
	v_mul_f32_e32 v19, v19, v179
	v_lshlrev_b32_e32 v178, 16, v114
	v_and_b32_e32 v179, 0xffff0000, v114
	v_fma_f32 v0, v0, v182, v4
	v_fma_f32 v1, v1, v183, v5
	v_rcp_f32_e32 v180, v17
	v_fma_f32 v4, v12, v178, v0
	v_fma_f32 v5, v13, v179, v1
	v_lshlrev_b32_e32 v178, 16, v107
	v_mul_f32_e32 v0, 0xbfb8aa3b, v5
	v_exp_f32_e32 v8, v0
	v_mul_f32_e32 v0, 0xbfb8aa3b, v4
	v_exp_f32_e32 v12, v0
	v_mul_f32_e32 v0, v176, v180
	v_mul_f32_e32 v1, v177, v181
	v_lshlrev_b32_e32 v180, 16, v103
	v_and_b32_e32 v181, 0xffff0000, v103
	v_and_b32_e32 v179, 0xffff0000, v107
	v_fma_f32 v10, v10, v180, 0
	v_fma_f32 v11, v11, v181, 0
	v_add_f32_e32 v8, 1.0, v8
	v_lshlrev_b32_e32 v176, 16, v111
	v_and_b32_e32 v177, 0xffff0000, v111
	v_fma_f32 v6, v6, v178, v10
	v_fma_f32 v7, v7, v179, v11
	v_rcp_f32_e32 v9, v8
	v_add_f32_e32 v8, 1.0, v12
	v_lshlrev_b32_e32 v12, 16, v115
	v_and_b32_e32 v13, 0xffff0000, v115
	v_fma_f32 v2, v2, v176, v6
	v_fma_f32 v3, v3, v177, v7
	ds_read_b32 v174, v146
	v_fma_f32 v6, v14, v12, v2
	v_fma_f32 v7, v15, v13, v3
	v_rcp_f32_e32 v8, v8
	v_mul_f32_e32 v2, 0xbfb8aa3b, v7
	v_exp_f32_e32 v2, v2
	v_mul_f32_e32 v3, 0xbfb8aa3b, v6
	v_exp_f32_e32 v3, v3
	v_mul_f32_e32 v4, v4, v8
	v_mul_f32_e32 v5, v5, v9
	v_add_f32_e32 v2, 1.0, v2
	v_rcp_f32_e32 v11, v2
	v_add_f32_e32 v2, 1.0, v3
	v_rcp_f32_e32 v10, v2
	s_waitcnt lgkmcnt(0)
	v_mul_f32_e32 v2, v174, v0
	v_mul_f32_e32 v3, v174, v1
	v_mul_f32_e32 v0, v174, v18
	v_mul_f32_e32 v1, v174, v19
	v_mul_f32_e32 v4, v174, v4
	v_mul_f32_e32 v5, v174, v5
	v_mul_f32_e32 v6, v6, v10
	v_mul_f32_e32 v7, v7, v11
	v_mov_b32_e32 v8, 0
	v_mul_f32_e32 v6, v174, v6
	v_mul_f32_e32 v7, v174, v7
	ds_write_b128 v162, v[0:3] offset:16896
	ds_write_b128 v162, v[4:7] offset:16912
	s_waitcnt lgkmcnt(0)
	s_barrier
; __device__ __forceinline__ void gdn_prep_item(const Params& p, unsigned char* lds, int item, u32x4 (&raw)[3][2][4], float& gpre, float& bpre, int next_item) {
;     ...
;         const int mat = wave >> 2, ti = (wave >> 1) & 1, tj = wave & 1, r32 = lane & 31, g = lane >> 5;
;         f32x16 acc;
; #pragma unroll
;         for (int r = 0; r < 16; ++r) acc[r] = 0.f;
;         if (tj <= ti && !(p.flags & 32)) {
;             const bf16_t* Xa = (mat ? qb : kb) + (32 * ti + r32) * 136 + 8 * g;
;             const bf16_t* Xb = kb + (32 * tj + r32) * 136 + 8 * g;
; #pragma unroll
;             for (int s = 0; s < 8; ++s) { const bf16x8 a = *(const bf16x8*)(Xa + 16 * s), bq = *(const bf16x8*)(Xb + 16 * s); acc = __builtin_amdgcn_mfma_f32_32x32x16_bf16(a, bq, acc, 0, 0, 0); }
;         }
	v_mov_b32_e32 v0, 0
	v_mov_b32_e32 v1, 0
	v_mov_b32_e32 v2, 0
	v_mov_b32_e32 v3, 0
	v_mov_b32_e32 v4, 0
	v_mov_b32_e32 v5, 0
	v_mov_b32_e32 v6, 0
	v_mov_b32_e32 v7, 0
	v_mov_b32_e32 v9, 0
	v_mov_b32_e32 v10, 0
	v_mov_b32_e32 v11, 0
	v_mov_b32_e32 v12, 0
	v_mov_b32_e32 v13, 0
	v_mov_b32_e32 v14, 0
	v_mov_b32_e32 v15, 0
	s_and_saveexec_b64 s[20:21], s[54:55]
	s_cbranch_execz .LBB0_108
	ds_read_b128 v[0:3], v147
	ds_read_b128 v[4:7], v149 offset:17408
	ds_read_b128 v[174:177], v147 offset:32
	ds_read_b128 v[178:181], v149 offset:17440
	s_waitcnt lgkmcnt(2)
	v_mfma_f32_32x32x16_bf16 v[0:15], v[0:3], v[4:7], 0
	s_waitcnt lgkmcnt(0)
	v_mfma_f32_32x32x16_bf16 v[0:15], v[174:177], v[178:181], v[0:15]
	ds_read_b128 v[174:177], v147 offset:64
	ds_read_b128 v[178:181], v149 offset:17472
	ds_read_b128 v[182:185], v147 offset:96
	ds_read_b128 v[186:189], v149 offset:17504
	s_waitcnt lgkmcnt(2)
	v_mfma_f32_32x32x16_bf16 v[0:15], v[174:177], v[178:181], v[0:15]
	s_waitcnt lgkmcnt(0)
	v_mfma_f32_32x32x16_bf16 v[0:15], v[182:185], v[186:189], v[0:15]
	ds_read_b128 v[174:177], v147 offset:128
	ds_read_b128 v[178:181], v149 offset:17536
	ds_read_b128 v[182:185], v147 offset:160
	ds_read_b128 v[186:189], v149 offset:17568
	s_waitcnt lgkmcnt(2)
	v_mfma_f32_32x32x16_bf16 v[0:15], v[174:177], v[178:181], v[0:15]
	s_waitcnt lgkmcnt(0)
	v_mfma_f32_32x32x16_bf16 v[0:15], v[182:185], v[186:189], v[0:15]
	ds_read_b128 v[174:177], v147 offset:192
	ds_read_b128 v[178:181], v149 offset:17600
	ds_read_b128 v[182:185], v147 offset:224
	ds_read_b128 v[186:189], v149 offset:17632
	s_waitcnt lgkmcnt(2)
	v_mfma_f32_32x32x16_bf16 v[0:15], v[174:177], v[178:181], v[0:15]
	s_waitcnt lgkmcnt(0)
	v_mfma_f32_32x32x16_bf16 v[0:15], v[182:185], v[186:189], v[0:15]

.LBB0_387:
	s_xor_b64 s[14:15], s[14:15], -1
	s_and_b64 s[10:11], s[14:15], s[10:11]
	s_xor_b64 s[12:13], s[10:11], -1
	s_andn2_b64 vcc, exec, s[18:19]
	v_sub_u32_e32 v0, v182, v166
	s_cbranch_vccnz .LBB0_392
	v_add_u32_e32 v90, v0, v204
	s_mov_b64 s[10:11], -1
	s_and_b64 vcc, exec, s[12:13]
	s_cbranch_vccz .LBB0_390
	v_mov_b32_e32 v89, v90
	s_add_i32 s10, 0, 0x22800
	v_cmp_lt_i32_e32 vcc, -1, v89
	s_and_b64 vcc, s[84:85], vcc
	v_min_i32_e32 v2, 0x7ff, v89
	v_cndmask_b32_e32 v2, 0, v2, vcc
	v_lshl_add_u32 v2, v2, 2, s10
	ds_read_b32 v2, v2
	v_add_u32_e32 v3, -1, v89
	v_add_u32_e32 v84, -2, v89
	v_add_u32_e32 v85, -3, v89
	v_subrev_u32_e32 v87, 17, v89
	s_waitcnt lgkmcnt(0)
	v_add_f32_e32 v2, v76, v2
	v_cndmask_b32_e32 v2, v219, v2, vcc
	v_cmp_lt_i32_e32 vcc, -1, v3
	s_and_b64 vcc, s[84:85], vcc
	v_min_i32_e32 v3, 0x7ff, v3
	v_cndmask_b32_e32 v3, 0, v3, vcc
	v_lshl_add_u32 v3, v3, 2, s10
	ds_read_b32 v3, v3
	s_waitcnt lgkmcnt(0)
	v_add_f32_e32 v3, v77, v3
	v_cndmask_b32_e32 v3, v219, v3, vcc
	v_cmp_lt_i32_e32 vcc, -1, v84
	s_and_b64 vcc, s[84:85], vcc
	v_min_i32_e32 v84, 0x7ff, v84
	v_cndmask_b32_e32 v84, 0, v84, vcc
	v_lshl_add_u32 v84, v84, 2, s10
	ds_read_b32 v84, v84
	v_max3_f32 v86, v2, s95, v3
	s_waitcnt lgkmcnt(0)
	v_add_f32_e32 v84, v78, v84
	v_cndmask_b32_e32 v84, v219, v84, vcc
	v_cmp_lt_i32_e32 vcc, -1, v85
	s_and_b64 vcc, s[84:85], vcc
	v_min_i32_e32 v85, 0x7ff, v85
	v_cndmask_b32_e32 v85, 0, v85, vcc
	v_lshl_add_u32 v85, v85, 2, s10
	ds_read_b32 v85, v85
	s_waitcnt lgkmcnt(0)
	v_add_f32_e32 v85, v79, v85
	v_cndmask_b32_e32 v85, v219, v85, vcc
	v_max3_f32 v88, v86, v84, v85
	v_add_u32_e32 v86, -16, v89
	v_cmp_lt_i32_e32 vcc, -1, v86
	s_and_b64 vcc, s[84:85], vcc
	v_min_i32_e32 v86, 0x7ff, v86
	v_cndmask_b32_e32 v86, 0, v86, vcc
	v_lshl_add_u32 v86, v86, 2, s10
	ds_read_b32 v86, v86
	s_waitcnt lgkmcnt(0)
	v_add_f32_e32 v86, v80, v86
	v_cndmask_b32_e32 v86, v219, v86, vcc
	v_cmp_lt_i32_e32 vcc, -1, v87
	s_and_b64 vcc, s[84:85], vcc
	v_min_i32_e32 v87, 0x7ff, v87
	v_cndmask_b32_e32 v87, 0, v87, vcc
	v_lshl_add_u32 v87, v87, 2, s10
	ds_read_b32 v87, v87
	s_waitcnt lgkmcnt(0)
	v_add_f32_e32 v87, v81, v87
	v_cndmask_b32_e32 v87, v219, v87, vcc
	v_max3_f32 v91, v88, v86, v87
	v_subrev_u32_e32 v88, 18, v89
	v_cmp_lt_i32_e32 vcc, -1, v88
	s_and_b64 vcc, s[84:85], vcc
	v_min_i32_e32 v88, 0x7ff, v88
	v_cndmask_b32_e32 v88, 0, v88, vcc
	v_lshl_add_u32 v88, v88, 2, s10
	ds_read_b32 v88, v88
	v_subrev_u32_e32 v89, 19, v89
	s_waitcnt lgkmcnt(0)
	v_add_f32_e32 v88, v82, v88
	v_cndmask_b32_e32 v88, v219, v88, vcc
	v_cmp_lt_i32_e32 vcc, -1, v89
	s_and_b64 vcc, s[84:85], vcc
	v_min_i32_e32 v89, 0x7ff, v89
	v_cndmask_b32_e32 v89, 0, v89, vcc
	v_lshl_add_u32 v89, v89, 2, s10
	ds_read_b32 v89, v89
	s_mov_b64 s[10:11], 0
	s_waitcnt lgkmcnt(0)
	v_add_f32_e32 v89, v83, v89
	v_cndmask_b32_e32 v89, v219, v89, vcc
	v_max3_f32 v91, v91, v88, v89
	v_mov_b32_e32 v83, v89
	v_mov_b32_e32 v82, v88
	v_mov_b32_e32 v81, v87
	v_mov_b32_e32 v80, v86
	v_mov_b32_e32 v79, v85
	v_mov_b32_e32 v78, v84
	v_mov_b32_e32 v77, v3
	v_mov_b32_e32 v76, v2
.LBB0_390:
	s_andn2_b64 vcc, exec, s[10:11]
	s_cbranch_vccnz .LBB0_392
	s_add_i32 s10, 0, 0x22800
	v_add_u32_e32 v3, -1, v90
	v_add_u32_e32 v84, -2, v90
	v_add_u32_e32 v85, -3, v90
	v_add_u32_e32 v86, -16, v90
	v_subrev_u32_e32 v87, 17, v90
	v_subrev_u32_e32 v88, 18, v90
	v_subrev_u32_e32 v89, 19, v90
	v_min_u32_e32 v2, 0x7ff, v90
	v_min_u32_e32 v3, 0x7ff, v3
	v_min_u32_e32 v84, 0x7ff, v84
	v_min_u32_e32 v85, 0x7ff, v85
	v_min_u32_e32 v86, 0x7ff, v86
	v_min_u32_e32 v87, 0x7ff, v87
	v_min_u32_e32 v88, 0x7ff, v88
	v_min_u32_e32 v89, 0x7ff, v89
	v_lshl_add_u32 v2, v2, 2, s10
	v_lshl_add_u32 v3, v3, 2, s10
	v_lshl_add_u32 v84, v84, 2, s10
	v_lshl_add_u32 v85, v85, 2, s10
	v_lshl_add_u32 v86, v86, 2, s10
	v_lshl_add_u32 v87, v87, 2, s10
	v_lshl_add_u32 v88, v88, 2, s10
	v_lshl_add_u32 v89, v89, 2, s10
	ds_read_b32 v2, v2
	ds_read_b32 v3, v3
	ds_read_b32 v84, v84
	ds_read_b32 v85, v85
	ds_read_b32 v86, v86
	ds_read_b32 v87, v87
	ds_read_b32 v88, v88
	ds_read_b32 v89, v89
	s_waitcnt lgkmcnt(6)
	v_pk_add_f32 v[2:3], v[76:77], v[2:3]
	s_waitcnt lgkmcnt(4)
	v_pk_add_f32 v[84:85], v[78:79], v[84:85]
	v_max3_f32 v76, v2, s95, v3
	v_max3_f32 v76, v76, v84, v85
	s_waitcnt lgkmcnt(2)
	v_pk_add_f32 v[86:87], v[80:81], v[86:87]
	s_waitcnt lgkmcnt(0)
	v_pk_add_f32 v[88:89], v[82:83], v[88:89]
	v_max3_f32 v76, v76, v86, v87
	v_max3_f32 v91, v76, v88, v89
	v_mov_b32_e32 v83, v89
	v_mov_b32_e32 v82, v88
	v_mov_b32_e32 v81, v87
	v_mov_b32_e32 v80, v86
	v_mov_b32_e32 v79, v85
	v_mov_b32_e32 v78, v84
	v_mov_b32_e32 v77, v3
	v_mov_b32_e32 v76, v2
.LBB0_392:
	v_and_b32_e32 v3, 64, v215
	v_xor_b32_e32 v2, 16, v215
	v_add_u32_e32 v3, 64, v3
	v_cmp_lt_i32_e32 vcc, v2, v3
	v_xor_b32_e32 v85, 32, v215
	v_max_f32_e32 v84, v91, v91
	v_cndmask_b32_e32 v2, v215, v2, vcc
	v_lshlrev_b32_e32 v179, 2, v2
	ds_bpermute_b32 v2, v179, v91
	v_cmp_lt_i32_e32 vcc, v85, v3
	s_xor_b64 s[20:21], s[8:9], -1
	s_mov_b64 s[18:19], -1
	v_cndmask_b32_e32 v3, v215, v85, vcc
	s_waitcnt lgkmcnt(0)
	v_max_f32_e32 v2, v2, v2
	v_max_f32_e32 v2, v84, v2
	v_lshlrev_b32_e32 v238, 2, v3
	ds_bpermute_b32 v3, v238, v2
	s_andn2_b64 vcc, exec, s[20:21]
	s_waitcnt lgkmcnt(0)
	v_max3_f32 v241, v2, v3, s95
	v_sub_f32_e32 v2, v76, v241
	v_exp_f32_e32 v108, v2
	v_sub_f32_e32 v2, v77, v241
	v_exp_f32_e32 v109, v2
	v_sub_f32_e32 v2, v78, v241
	v_exp_f32_e32 v110, v2
	v_sub_f32_e32 v2, v79, v241
	v_exp_f32_e32 v132, v2
	v_sub_f32_e32 v2, v80, v241
	v_exp_f32_e32 v133, v2
	v_sub_f32_e32 v2, v81, v241
	v_exp_f32_e32 v134, v2
	v_sub_f32_e32 v2, v82, v241
	v_exp_f32_e32 v135, v2
	v_sub_f32_e32 v2, v83, v241
	v_exp_f32_e32 v136, v2
	v_cndmask_b32_e64 v2, 0, 1, s[20:21]
	v_cmp_neq_f32_e64 s[10:11], s95, v241
	v_cmp_ne_u32_e64 s[8:9], 1, v2
	v_cvt_pk_bf16_f32 v104, v108, v109
	v_cvt_pk_bf16_f32 v105, v110, v132
	v_cvt_pk_bf16_f32 v106, v133, v134
	v_cvt_pk_bf16_f32 v107, v135, v136
	s_cbranch_vccnz .LBB0_394
	v_max3_f32 v2, v68, v69, v70
	v_max3_f32 v2, v2, v71, s95
	v_max3_f32 v3, v72, v73, v74
	v_max3_f32 v83, v2, v3, v75
	s_mov_b64 s[18:19], 0
	v_mov_b32_e32 v81, v75
	v_mov_b32_e32 v80, v74
	v_mov_b32_e32 v79, v73
	v_mov_b32_e32 v78, v72
	v_mov_b32_e32 v77, v71
	v_mov_b32_e32 v76, v70
	v_mov_b32_e32 v3, v69
	v_mov_b32_e32 v2, v68

.LBB0_408:
	s_andn2_b64 vcc, exec, s[14:15]
	s_cbranch_vccnz .LBB0_413
	v_add_u32_e32 v242, v0, v207
	s_andn2_b64 vcc, exec, s[12:13]
	s_mov_b64 s[14:15], -1
	s_cbranch_vccnz .LBB0_411
	v_mov_b32_e32 v193, v242
	s_add_i32 s14, 0, 0x22800
	v_cmp_lt_i32_e32 vcc, -1, v193
	s_and_b64 vcc, s[84:85], vcc
	v_min_i32_e32 v2, 0x7ff, v193
	v_cndmask_b32_e32 v2, 0, v2, vcc
	v_lshl_add_u32 v2, v2, 2, s14
	ds_read_b32 v2, v2
	v_add_u32_e32 v3, -1, v193
	v_add_u32_e32 v188, -2, v193
	v_add_u32_e32 v189, -3, v193
	v_subrev_u32_e32 v191, 17, v193
	s_waitcnt lgkmcnt(0)
	v_add_f32_e32 v2, v140, v2
	v_cndmask_b32_e32 v2, v219, v2, vcc
	v_cmp_lt_i32_e32 vcc, -1, v3
	s_and_b64 vcc, s[84:85], vcc
	v_min_i32_e32 v3, 0x7ff, v3
	v_cndmask_b32_e32 v3, 0, v3, vcc
	v_lshl_add_u32 v3, v3, 2, s14
	ds_read_b32 v3, v3
	s_waitcnt lgkmcnt(0)
	v_add_f32_e32 v3, v141, v3
	v_cndmask_b32_e32 v3, v219, v3, vcc
	v_cmp_lt_i32_e32 vcc, -1, v188
	s_and_b64 vcc, s[84:85], vcc
	v_min_i32_e32 v188, 0x7ff, v188
	v_cndmask_b32_e32 v188, 0, v188, vcc
	v_lshl_add_u32 v188, v188, 2, s14
	ds_read_b32 v188, v188
	v_max3_f32 v190, v2, s95, v3
	s_waitcnt lgkmcnt(0)
	v_add_f32_e32 v188, v142, v188
	v_cndmask_b32_e32 v188, v219, v188, vcc
	v_cmp_lt_i32_e32 vcc, -1, v189
	s_and_b64 vcc, s[84:85], vcc
	v_min_i32_e32 v189, 0x7ff, v189
	v_cndmask_b32_e32 v189, 0, v189, vcc
	v_lshl_add_u32 v189, v189, 2, s14
	ds_read_b32 v189, v189
	s_waitcnt lgkmcnt(0)
	v_add_f32_e32 v189, v143, v189
	v_cndmask_b32_e32 v189, v219, v189, vcc
	v_max3_f32 v192, v190, v188, v189
	v_add_u32_e32 v190, -16, v193
	v_cmp_lt_i32_e32 vcc, -1, v190
	s_and_b64 vcc, s[84:85], vcc
	v_min_i32_e32 v190, 0x7ff, v190
	v_cndmask_b32_e32 v190, 0, v190, vcc
	v_lshl_add_u32 v190, v190, 2, s14
	ds_read_b32 v190, v190
	s_waitcnt lgkmcnt(0)
	v_add_f32_e32 v190, v144, v190
	v_cndmask_b32_e32 v190, v219, v190, vcc
	v_cmp_lt_i32_e32 vcc, -1, v191
	s_and_b64 vcc, s[84:85], vcc
	v_min_i32_e32 v191, 0x7ff, v191
	v_cndmask_b32_e32 v191, 0, v191, vcc
	v_lshl_add_u32 v191, v191, 2, s14
	ds_read_b32 v191, v191
	s_waitcnt lgkmcnt(0)
	v_add_f32_e32 v191, v145, v191
	v_cndmask_b32_e32 v191, v219, v191, vcc
	v_max3_f32 v243, v192, v190, v191
	v_subrev_u32_e32 v192, 18, v193
	v_cmp_lt_i32_e32 vcc, -1, v192
	s_and_b64 vcc, s[84:85], vcc
	v_min_i32_e32 v192, 0x7ff, v192
	v_cndmask_b32_e32 v192, 0, v192, vcc
	v_lshl_add_u32 v192, v192, 2, s14
	ds_read_b32 v192, v192
	v_subrev_u32_e32 v193, 19, v193
	s_waitcnt lgkmcnt(0)
	v_add_f32_e32 v192, v146, v192
	v_cndmask_b32_e32 v192, v219, v192, vcc
	v_cmp_lt_i32_e32 vcc, -1, v193
	s_and_b64 vcc, s[84:85], vcc
	v_min_i32_e32 v193, 0x7ff, v193
	v_cndmask_b32_e32 v193, 0, v193, vcc
	v_lshl_add_u32 v193, v193, 2, s14
	ds_read_b32 v193, v193
	s_mov_b64 s[14:15], 0
	s_waitcnt lgkmcnt(0)
	v_add_f32_e32 v193, v147, v193
	v_cndmask_b32_e32 v193, v219, v193, vcc
	v_max3_f32 v243, v243, v192, v193
	v_mov_b32_e32 v147, v193
	v_mov_b32_e32 v146, v192
	v_mov_b32_e32 v145, v191
	v_mov_b32_e32 v144, v190
	v_mov_b32_e32 v143, v189
	v_mov_b32_e32 v142, v188
	v_mov_b32_e32 v141, v3
	v_mov_b32_e32 v140, v2
.LBB0_411:
	s_andn2_b64 vcc, exec, s[14:15]
	s_cbranch_vccnz .LBB0_413
	s_add_i32 s14, 0, 0x22800
	v_lshl_add_u32 v2, v242, 2, s14
	v_add_u32_e32 v3, -4, v2
	v_add_u32_e32 v188, -8, v2
	v_add_u32_e32 v189, -12, v2
	v_add_u32_e32 v190, 0xffffffc0, v2
	v_subrev_u32_e32 v191, 0x44, v2
	v_subrev_u32_e32 v192, 0x48, v2
	v_subrev_u32_e32 v193, 0x4c, v2
	v_min_u32_e32 v2, 0x247fc, v2
	v_min_u32_e32 v3, 0x247fc, v3
	v_min_u32_e32 v188, 0x247fc, v188
	v_min_u32_e32 v189, 0x247fc, v189
	v_min_u32_e32 v190, 0x247fc, v190
	v_min_u32_e32 v191, 0x247fc, v191
	v_min_u32_e32 v192, 0x247fc, v192
	v_min_u32_e32 v193, 0x247fc, v193
	ds_read_b32 v2, v2
	ds_read_b32 v3, v3
	ds_read_b32 v188, v188
	ds_read_b32 v189, v189
	ds_read_b32 v190, v190
	ds_read_b32 v191, v191
	ds_read_b32 v192, v192
	ds_read_b32 v193, v193
	s_waitcnt lgkmcnt(6)
	v_pk_add_f32 v[2:3], v[140:141], v[2:3]
	s_waitcnt lgkmcnt(4)
	v_pk_add_f32 v[188:189], v[142:143], v[188:189]
	v_max3_f32 v140, v2, s95, v3
	v_max3_f32 v140, v140, v188, v189
	s_waitcnt lgkmcnt(2)
	v_pk_add_f32 v[190:191], v[144:145], v[190:191]
	s_waitcnt lgkmcnt(0)
	v_pk_add_f32 v[192:193], v[146:147], v[192:193]
	v_max3_f32 v140, v140, v190, v191
	v_max3_f32 v243, v140, v192, v193
	v_mov_b32_e32 v147, v193
	v_mov_b32_e32 v146, v192
	v_mov_b32_e32 v145, v191
	v_mov_b32_e32 v144, v190
	v_mov_b32_e32 v143, v189
	v_mov_b32_e32 v142, v188
	v_mov_b32_e32 v141, v3
	v_mov_b32_e32 v140, v2
.LBB0_413:
	v_mov_b32_e32 v2, v243
	v_mov_b32_e32 v3, v243
	s_nop 1
	v_permlane16_swap_b32_e32 v2, v3
	v_max_f32_e32 v2, v2, v3
	v_mov_b32_e32 v3, v2
	s_nop 1
	v_permlane32_swap_b32_e32 v2, v3
	v_max3_f32 v242, v241, v2, v3
	v_cmp_neq_f32_e32 vcc, v242, v241
	s_cbranch_vccz .LBB0_415
	v_sub_f32_e32 v2, v241, v242
	v_exp_f32_e32 v2, v2
	s_nop 0
	v_pk_mul_f32 v[130:131], v[130:131], v[2:3] op_sel_hi:[1,0]
	v_pk_mul_f32 v[128:129], v[128:129], v[2:3] op_sel_hi:[1,0]
	v_pk_mul_f32 v[126:127], v[126:127], v[2:3] op_sel_hi:[1,0]
	v_pk_mul_f32 v[124:125], v[124:125], v[2:3] op_sel_hi:[1,0]
	v_pk_mul_f32 v[122:123], v[122:123], v[2:3] op_sel_hi:[1,0]
	v_pk_mul_f32 v[120:121], v[120:121], v[2:3] op_sel_hi:[1,0]
	v_pk_mul_f32 v[118:119], v[118:119], v[2:3] op_sel_hi:[1,0]
	v_pk_mul_f32 v[116:117], v[116:117], v[2:3] op_sel_hi:[1,0]
	v_pk_mul_f32 v[114:115], v[114:115], v[2:3] op_sel_hi:[1,0]
	v_pk_mul_f32 v[112:113], v[112:113], v[2:3] op_sel_hi:[1,0]
	v_pk_mul_f32 v[102:103], v[102:103], v[2:3] op_sel_hi:[1,0]
	v_pk_mul_f32 v[100:101], v[100:101], v[2:3] op_sel_hi:[1,0]
	v_pk_mul_f32 v[110:111], v[110:111], v[2:3] op_sel_hi:[1,0]
	v_pk_mul_f32 v[108:109], v[108:109], v[2:3] op_sel_hi:[1,0]
	v_pk_mul_f32 v[106:107], v[106:107], v[2:3] op_sel_hi:[1,0]
	v_pk_mul_f32 v[104:105], v[104:105], v[2:3] op_sel_hi:[1,0]
	v_mul_f32_e32 v183, v183, v2
.LBB0_415:
	v_sub_f32_e32 v2, v140, v242
	v_exp_f32_e32 v246, v2
	v_sub_f32_e32 v2, v141, v242
	v_exp_f32_e32 v241, v2
	v_sub_f32_e32 v2, v142, v242
	v_exp_f32_e32 v243, v2
	v_sub_f32_e32 v2, v143, v242
	v_exp_f32_e32 v244, v2
	v_sub_f32_e32 v2, v144, v242
	v_exp_f32_e32 v245, v2
	v_sub_f32_e32 v2, v145, v242
	v_exp_f32_e32 v247, v2
	v_sub_f32_e32 v2, v146, v242
	v_exp_f32_e32 v190, v2
	v_sub_f32_e32 v2, v147, v242
	v_exp_f32_e32 v191, v2
	s_and_b64 vcc, exec, s[8:9]
	s_mov_b64 s[14:15], -1
	v_cvt_pk_bf16_f32 v140, v246, v241
	v_cvt_pk_bf16_f32 v141, v243, v244
	v_cvt_pk_bf16_f32 v142, v245, v247
	v_cvt_pk_bf16_f32 v143, v190, v191
	s_cbranch_vccnz .LBB0_417
	v_max3_f32 v2, v132, v133, v134
	v_max3_f32 v2, v2, v135, s95
	v_max3_f32 v3, v136, v137, v138
	v_max3_f32 v193, v2, v3, v139
	s_mov_b64 s[14:15], 0
	v_mov_b32_e32 v189, v139
	v_mov_b32_e32 v188, v138
	v_mov_b32_e32 v147, v137
	v_mov_b32_e32 v146, v136
	v_mov_b32_e32 v145, v135
	v_mov_b32_e32 v144, v134
	v_mov_b32_e32 v3, v133
	v_mov_b32_e32 v2, v132

.LBB0_427:
	s_andn2_b64 vcc, exec, s[14:15]
	s_cbranch_vccnz .LBB0_432
	v_add_u32_e32 v242, v0, v208
	s_andn2_b64 vcc, exec, s[12:13]
	s_mov_b64 s[14:15], -1
	s_cbranch_vccnz .LBB0_430
	v_mov_b32_e32 v193, v242
	s_add_i32 s14, 0, 0x22800
	v_cmp_lt_i32_e32 vcc, -1, v193
	s_and_b64 vcc, s[84:85], vcc
	v_min_i32_e32 v2, 0x7ff, v193
	v_cndmask_b32_e32 v2, 0, v2, vcc
	v_lshl_add_u32 v2, v2, 2, s14
	ds_read_b32 v2, v2
	v_add_u32_e32 v3, -1, v193
	v_add_u32_e32 v188, -2, v193
	v_add_u32_e32 v189, -3, v193
	v_subrev_u32_e32 v191, 17, v193
	s_waitcnt lgkmcnt(0)
	v_add_f32_e32 v2, v140, v2
	v_cndmask_b32_e32 v2, v219, v2, vcc
	v_cmp_lt_i32_e32 vcc, -1, v3
	s_and_b64 vcc, s[84:85], vcc
	v_min_i32_e32 v3, 0x7ff, v3
	v_cndmask_b32_e32 v3, 0, v3, vcc
	v_lshl_add_u32 v3, v3, 2, s14
	ds_read_b32 v3, v3
	s_waitcnt lgkmcnt(0)
	v_add_f32_e32 v3, v141, v3
	v_cndmask_b32_e32 v3, v219, v3, vcc
	v_cmp_lt_i32_e32 vcc, -1, v188
	s_and_b64 vcc, s[84:85], vcc
	v_min_i32_e32 v188, 0x7ff, v188
	v_cndmask_b32_e32 v188, 0, v188, vcc
	v_lshl_add_u32 v188, v188, 2, s14
	ds_read_b32 v188, v188
	v_max3_f32 v190, v2, s95, v3
	s_waitcnt lgkmcnt(0)
	v_add_f32_e32 v188, v142, v188
	v_cndmask_b32_e32 v188, v219, v188, vcc
	v_cmp_lt_i32_e32 vcc, -1, v189
	s_and_b64 vcc, s[84:85], vcc
	v_min_i32_e32 v189, 0x7ff, v189
	v_cndmask_b32_e32 v189, 0, v189, vcc
	v_lshl_add_u32 v189, v189, 2, s14
	ds_read_b32 v189, v189
	s_waitcnt lgkmcnt(0)
	v_add_f32_e32 v189, v143, v189
	v_cndmask_b32_e32 v189, v219, v189, vcc
	v_max3_f32 v192, v190, v188, v189
	v_add_u32_e32 v190, -16, v193
	v_cmp_lt_i32_e32 vcc, -1, v190
	s_and_b64 vcc, s[84:85], vcc
	v_min_i32_e32 v190, 0x7ff, v190
	v_cndmask_b32_e32 v190, 0, v190, vcc
	v_lshl_add_u32 v190, v190, 2, s14
	ds_read_b32 v190, v190
	s_waitcnt lgkmcnt(0)
	v_add_f32_e32 v190, v144, v190
	v_cndmask_b32_e32 v190, v219, v190, vcc
	v_cmp_lt_i32_e32 vcc, -1, v191
	s_and_b64 vcc, s[84:85], vcc
	v_min_i32_e32 v191, 0x7ff, v191
	v_cndmask_b32_e32 v191, 0, v191, vcc
	v_lshl_add_u32 v191, v191, 2, s14
	ds_read_b32 v191, v191
	s_waitcnt lgkmcnt(0)
	v_add_f32_e32 v191, v145, v191
	v_cndmask_b32_e32 v191, v219, v191, vcc
	v_max3_f32 v243, v192, v190, v191
	v_subrev_u32_e32 v192, 18, v193
	v_cmp_lt_i32_e32 vcc, -1, v192
	s_and_b64 vcc, s[84:85], vcc
	v_min_i32_e32 v192, 0x7ff, v192
	v_cndmask_b32_e32 v192, 0, v192, vcc
	v_lshl_add_u32 v192, v192, 2, s14
	ds_read_b32 v192, v192
	v_subrev_u32_e32 v193, 19, v193
	s_waitcnt lgkmcnt(0)
	v_add_f32_e32 v192, v146, v192
	v_cndmask_b32_e32 v192, v219, v192, vcc
	v_cmp_lt_i32_e32 vcc, -1, v193
	s_and_b64 vcc, s[84:85], vcc
	v_min_i32_e32 v193, 0x7ff, v193
	v_cndmask_b32_e32 v193, 0, v193, vcc
	v_lshl_add_u32 v193, v193, 2, s14
	ds_read_b32 v193, v193
	s_mov_b64 s[14:15], 0
	s_waitcnt lgkmcnt(0)
	v_add_f32_e32 v193, v147, v193
	v_cndmask_b32_e32 v193, v219, v193, vcc
	v_max3_f32 v243, v243, v192, v193
	v_mov_b32_e32 v147, v193
	v_mov_b32_e32 v146, v192
	v_mov_b32_e32 v145, v191
	v_mov_b32_e32 v144, v190
	v_mov_b32_e32 v143, v189
	v_mov_b32_e32 v142, v188
	v_mov_b32_e32 v141, v3
	v_mov_b32_e32 v140, v2

.LBB0_446:
	s_andn2_b64 vcc, exec, s[14:15]
	s_cbranch_vccnz .LBB0_451
	v_add_u32_e32 v242, v0, v209
	s_andn2_b64 vcc, exec, s[12:13]
	s_mov_b64 s[14:15], -1
	s_cbranch_vccnz .LBB0_449
	v_mov_b32_e32 v193, v242
	s_add_i32 s14, 0, 0x22800
	v_cmp_lt_i32_e32 vcc, -1, v193
	s_and_b64 vcc, s[84:85], vcc
	v_min_i32_e32 v2, 0x7ff, v193
	v_cndmask_b32_e32 v2, 0, v2, vcc
	v_lshl_add_u32 v2, v2, 2, s14
	ds_read_b32 v2, v2
	v_add_u32_e32 v3, -1, v193
	v_add_u32_e32 v188, -2, v193
	v_add_u32_e32 v189, -3, v193
	v_subrev_u32_e32 v191, 17, v193
	s_waitcnt lgkmcnt(0)
	v_add_f32_e32 v2, v140, v2
	v_cndmask_b32_e32 v2, v219, v2, vcc
	v_cmp_lt_i32_e32 vcc, -1, v3
	s_and_b64 vcc, s[84:85], vcc
	v_min_i32_e32 v3, 0x7ff, v3
	v_cndmask_b32_e32 v3, 0, v3, vcc
	v_lshl_add_u32 v3, v3, 2, s14
	ds_read_b32 v3, v3
	s_waitcnt lgkmcnt(0)
	v_add_f32_e32 v3, v141, v3
	v_cndmask_b32_e32 v3, v219, v3, vcc
	v_cmp_lt_i32_e32 vcc, -1, v188
	s_and_b64 vcc, s[84:85], vcc
	v_min_i32_e32 v188, 0x7ff, v188
	v_cndmask_b32_e32 v188, 0, v188, vcc
	v_lshl_add_u32 v188, v188, 2, s14
	ds_read_b32 v188, v188
	v_max3_f32 v190, v2, s95, v3
	s_waitcnt lgkmcnt(0)
	v_add_f32_e32 v188, v142, v188
	v_cndmask_b32_e32 v188, v219, v188, vcc
	v_cmp_lt_i32_e32 vcc, -1, v189
	s_and_b64 vcc, s[84:85], vcc
	v_min_i32_e32 v189, 0x7ff, v189
	v_cndmask_b32_e32 v189, 0, v189, vcc
	v_lshl_add_u32 v189, v189, 2, s14
	ds_read_b32 v189, v189
	s_waitcnt lgkmcnt(0)
	v_add_f32_e32 v189, v143, v189
	v_cndmask_b32_e32 v189, v219, v189, vcc
	v_max3_f32 v192, v190, v188, v189
	v_add_u32_e32 v190, -16, v193
	v_cmp_lt_i32_e32 vcc, -1, v190
	s_and_b64 vcc, s[84:85], vcc
	v_min_i32_e32 v190, 0x7ff, v190
	v_cndmask_b32_e32 v190, 0, v190, vcc
	v_lshl_add_u32 v190, v190, 2, s14
	ds_read_b32 v190, v190
	s_waitcnt lgkmcnt(0)
	v_add_f32_e32 v190, v144, v190
	v_cndmask_b32_e32 v190, v219, v190, vcc
	v_cmp_lt_i32_e32 vcc, -1, v191
	s_and_b64 vcc, s[84:85], vcc
	v_min_i32_e32 v191, 0x7ff, v191
	v_cndmask_b32_e32 v191, 0, v191, vcc
	v_lshl_add_u32 v191, v191, 2, s14
	ds_read_b32 v191, v191
	s_waitcnt lgkmcnt(0)
	v_add_f32_e32 v191, v145, v191
	v_cndmask_b32_e32 v191, v219, v191, vcc
	v_max3_f32 v243, v192, v190, v191
	v_subrev_u32_e32 v192, 18, v193
	v_cmp_lt_i32_e32 vcc, -1, v192
	s_and_b64 vcc, s[84:85], vcc
	v_min_i32_e32 v192, 0x7ff, v192
	v_cndmask_b32_e32 v192, 0, v192, vcc
	v_lshl_add_u32 v192, v192, 2, s14
	ds_read_b32 v192, v192
	v_subrev_u32_e32 v193, 19, v193
	s_waitcnt lgkmcnt(0)
	v_add_f32_e32 v192, v146, v192
	v_cndmask_b32_e32 v192, v219, v192, vcc
	v_cmp_lt_i32_e32 vcc, -1, v193
	s_and_b64 vcc, s[84:85], vcc
	v_min_i32_e32 v193, 0x7ff, v193
	v_cndmask_b32_e32 v193, 0, v193, vcc
	v_lshl_add_u32 v193, v193, 2, s14
	ds_read_b32 v193, v193
	s_mov_b64 s[14:15], 0
	s_waitcnt lgkmcnt(0)
	v_add_f32_e32 v193, v147, v193
	v_cndmask_b32_e32 v193, v219, v193, vcc
	v_max3_f32 v243, v243, v192, v193
	v_mov_b32_e32 v147, v193
	v_mov_b32_e32 v146, v192
	v_mov_b32_e32 v145, v191
	v_mov_b32_e32 v144, v190
	v_mov_b32_e32 v143, v189
	v_mov_b32_e32 v142, v188
	v_mov_b32_e32 v141, v3
	v_mov_b32_e32 v140, v2

.LBB0_465:
	s_andn2_b64 vcc, exec, s[14:15]
	s_cbranch_vccnz .LBB0_470
	v_add_u32_e32 v242, v0, v210
	s_andn2_b64 vcc, exec, s[12:13]
	s_mov_b64 s[14:15], -1
	s_cbranch_vccnz .LBB0_468
	v_mov_b32_e32 v193, v242
	s_add_i32 s14, 0, 0x22800
	v_cmp_lt_i32_e32 vcc, -1, v193
	s_and_b64 vcc, s[84:85], vcc
	v_min_i32_e32 v2, 0x7ff, v193
	v_cndmask_b32_e32 v2, 0, v2, vcc
	v_lshl_add_u32 v2, v2, 2, s14
	ds_read_b32 v2, v2
	v_add_u32_e32 v3, -1, v193
	v_add_u32_e32 v188, -2, v193
	v_add_u32_e32 v189, -3, v193
	v_subrev_u32_e32 v191, 17, v193
	s_waitcnt lgkmcnt(0)
	v_add_f32_e32 v2, v140, v2
	v_cndmask_b32_e32 v2, v219, v2, vcc
	v_cmp_lt_i32_e32 vcc, -1, v3
	s_and_b64 vcc, s[84:85], vcc
	v_min_i32_e32 v3, 0x7ff, v3
	v_cndmask_b32_e32 v3, 0, v3, vcc
	v_lshl_add_u32 v3, v3, 2, s14
	ds_read_b32 v3, v3
	s_waitcnt lgkmcnt(0)
	v_add_f32_e32 v3, v141, v3
	v_cndmask_b32_e32 v3, v219, v3, vcc
	v_cmp_lt_i32_e32 vcc, -1, v188
	s_and_b64 vcc, s[84:85], vcc
	v_min_i32_e32 v188, 0x7ff, v188
	v_cndmask_b32_e32 v188, 0, v188, vcc
	v_lshl_add_u32 v188, v188, 2, s14
	ds_read_b32 v188, v188
	v_max3_f32 v190, v2, s95, v3
	s_waitcnt lgkmcnt(0)
	v_add_f32_e32 v188, v142, v188
	v_cndmask_b32_e32 v188, v219, v188, vcc
	v_cmp_lt_i32_e32 vcc, -1, v189
	s_and_b64 vcc, s[84:85], vcc
	v_min_i32_e32 v189, 0x7ff, v189
	v_cndmask_b32_e32 v189, 0, v189, vcc
	v_lshl_add_u32 v189, v189, 2, s14
	ds_read_b32 v189, v189
	s_waitcnt lgkmcnt(0)
	v_add_f32_e32 v189, v143, v189
	v_cndmask_b32_e32 v189, v219, v189, vcc
	v_max3_f32 v192, v190, v188, v189
	v_add_u32_e32 v190, -16, v193
	v_cmp_lt_i32_e32 vcc, -1, v190
	s_and_b64 vcc, s[84:85], vcc
	v_min_i32_e32 v190, 0x7ff, v190
	v_cndmask_b32_e32 v190, 0, v190, vcc
	v_lshl_add_u32 v190, v190, 2, s14
	ds_read_b32 v190, v190
	s_waitcnt lgkmcnt(0)
	v_add_f32_e32 v190, v144, v190
	v_cndmask_b32_e32 v190, v219, v190, vcc
	v_cmp_lt_i32_e32 vcc, -1, v191
	s_and_b64 vcc, s[84:85], vcc
	v_min_i32_e32 v191, 0x7ff, v191
	v_cndmask_b32_e32 v191, 0, v191, vcc
	v_lshl_add_u32 v191, v191, 2, s14
	ds_read_b32 v191, v191
	s_waitcnt lgkmcnt(0)
	v_add_f32_e32 v191, v145, v191
	v_cndmask_b32_e32 v191, v219, v191, vcc
	v_max3_f32 v243, v192, v190, v191
	v_subrev_u32_e32 v192, 18, v193
	v_cmp_lt_i32_e32 vcc, -1, v192
	s_and_b64 vcc, s[84:85], vcc
	v_min_i32_e32 v192, 0x7ff, v192
	v_cndmask_b32_e32 v192, 0, v192, vcc
	v_lshl_add_u32 v192, v192, 2, s14
	ds_read_b32 v192, v192
	v_subrev_u32_e32 v193, 19, v193
	s_waitcnt lgkmcnt(0)
	v_add_f32_e32 v192, v146, v192
	v_cndmask_b32_e32 v192, v219, v192, vcc
	v_cmp_lt_i32_e32 vcc, -1, v193
	s_and_b64 vcc, s[84:85], vcc
	v_min_i32_e32 v193, 0x7ff, v193
	v_cndmask_b32_e32 v193, 0, v193, vcc
	v_lshl_add_u32 v193, v193, 2, s14
	ds_read_b32 v193, v193
	s_mov_b64 s[14:15], 0
	s_waitcnt lgkmcnt(0)
	v_add_f32_e32 v193, v147, v193
	v_cndmask_b32_e32 v193, v219, v193, vcc
	v_max3_f32 v243, v243, v192, v193
	v_mov_b32_e32 v147, v193
	v_mov_b32_e32 v146, v192
	v_mov_b32_e32 v145, v191
	v_mov_b32_e32 v144, v190
	v_mov_b32_e32 v143, v189
	v_mov_b32_e32 v142, v188
	v_mov_b32_e32 v141, v3
	v_mov_b32_e32 v140, v2

.LBB0_484:
	s_andn2_b64 vcc, exec, s[14:15]
	s_cbranch_vccnz .LBB0_489
	v_add_u32_e32 v242, v0, v211
	s_andn2_b64 vcc, exec, s[12:13]
	s_mov_b64 s[14:15], -1
	s_cbranch_vccnz .LBB0_487
	v_mov_b32_e32 v193, v242
	s_add_i32 s14, 0, 0x22800
	v_cmp_lt_i32_e32 vcc, -1, v193
	s_and_b64 vcc, s[84:85], vcc
	v_min_i32_e32 v2, 0x7ff, v193
	v_cndmask_b32_e32 v2, 0, v2, vcc
	v_lshl_add_u32 v2, v2, 2, s14
	ds_read_b32 v2, v2
	v_add_u32_e32 v3, -1, v193
	v_add_u32_e32 v188, -2, v193
	v_add_u32_e32 v189, -3, v193
	v_subrev_u32_e32 v191, 17, v193
	s_waitcnt lgkmcnt(0)
	v_add_f32_e32 v2, v140, v2
	v_cndmask_b32_e32 v2, v219, v2, vcc
	v_cmp_lt_i32_e32 vcc, -1, v3
	s_and_b64 vcc, s[84:85], vcc
	v_min_i32_e32 v3, 0x7ff, v3
	v_cndmask_b32_e32 v3, 0, v3, vcc
	v_lshl_add_u32 v3, v3, 2, s14
	ds_read_b32 v3, v3
	s_waitcnt lgkmcnt(0)
	v_add_f32_e32 v3, v141, v3
	v_cndmask_b32_e32 v3, v219, v3, vcc
	v_cmp_lt_i32_e32 vcc, -1, v188
	s_and_b64 vcc, s[84:85], vcc
	v_min_i32_e32 v188, 0x7ff, v188
	v_cndmask_b32_e32 v188, 0, v188, vcc
	v_lshl_add_u32 v188, v188, 2, s14
	ds_read_b32 v188, v188
	v_max3_f32 v190, v2, s95, v3
	s_waitcnt lgkmcnt(0)
	v_add_f32_e32 v188, v142, v188
	v_cndmask_b32_e32 v188, v219, v188, vcc
	v_cmp_lt_i32_e32 vcc, -1, v189
	s_and_b64 vcc, s[84:85], vcc
	v_min_i32_e32 v189, 0x7ff, v189
	v_cndmask_b32_e32 v189, 0, v189, vcc
	v_lshl_add_u32 v189, v189, 2, s14
	ds_read_b32 v189, v189
	s_waitcnt lgkmcnt(0)
	v_add_f32_e32 v189, v143, v189
	v_cndmask_b32_e32 v189, v219, v189, vcc
	v_max3_f32 v192, v190, v188, v189
	v_add_u32_e32 v190, -16, v193
	v_cmp_lt_i32_e32 vcc, -1, v190
	s_and_b64 vcc, s[84:85], vcc
	v_min_i32_e32 v190, 0x7ff, v190
	v_cndmask_b32_e32 v190, 0, v190, vcc
	v_lshl_add_u32 v190, v190, 2, s14
	ds_read_b32 v190, v190
	s_waitcnt lgkmcnt(0)
	v_add_f32_e32 v190, v144, v190
	v_cndmask_b32_e32 v190, v219, v190, vcc
	v_cmp_lt_i32_e32 vcc, -1, v191
	s_and_b64 vcc, s[84:85], vcc
	v_min_i32_e32 v191, 0x7ff, v191
	v_cndmask_b32_e32 v191, 0, v191, vcc
	v_lshl_add_u32 v191, v191, 2, s14
	ds_read_b32 v191, v191
	s_waitcnt lgkmcnt(0)
	v_add_f32_e32 v191, v145, v191
	v_cndmask_b32_e32 v191, v219, v191, vcc
	v_max3_f32 v243, v192, v190, v191
	v_subrev_u32_e32 v192, 18, v193
	v_cmp_lt_i32_e32 vcc, -1, v192
	s_and_b64 vcc, s[84:85], vcc
	v_min_i32_e32 v192, 0x7ff, v192
	v_cndmask_b32_e32 v192, 0, v192, vcc
	v_lshl_add_u32 v192, v192, 2, s14
	ds_read_b32 v192, v192
	v_subrev_u32_e32 v193, 19, v193
	s_waitcnt lgkmcnt(0)
	v_add_f32_e32 v192, v146, v192
	v_cndmask_b32_e32 v192, v219, v192, vcc
	v_cmp_lt_i32_e32 vcc, -1, v193
	s_and_b64 vcc, s[84:85], vcc
	v_min_i32_e32 v193, 0x7ff, v193
	v_cndmask_b32_e32 v193, 0, v193, vcc
	v_lshl_add_u32 v193, v193, 2, s14
	ds_read_b32 v193, v193
	s_mov_b64 s[14:15], 0
	s_waitcnt lgkmcnt(0)
	v_add_f32_e32 v193, v147, v193
	v_cndmask_b32_e32 v193, v219, v193, vcc
	v_max3_f32 v243, v243, v192, v193
	v_mov_b32_e32 v147, v193
	v_mov_b32_e32 v146, v192
	v_mov_b32_e32 v145, v191
	v_mov_b32_e32 v144, v190
	v_mov_b32_e32 v143, v189
	v_mov_b32_e32 v142, v188
	v_mov_b32_e32 v141, v3
	v_mov_b32_e32 v140, v2

.LBB0_503:
	s_andn2_b64 vcc, exec, s[14:15]
	s_cbranch_vccnz .LBB0_508
	v_add_u32_e32 v242, v0, v212
	s_andn2_b64 vcc, exec, s[12:13]
	s_mov_b64 s[14:15], -1
	s_cbranch_vccnz .LBB0_506
	v_mov_b32_e32 v193, v242
	s_add_i32 s14, 0, 0x22800
	v_cmp_lt_i32_e32 vcc, -1, v193
	s_and_b64 vcc, s[84:85], vcc
	v_min_i32_e32 v2, 0x7ff, v193
	v_cndmask_b32_e32 v2, 0, v2, vcc
	v_lshl_add_u32 v2, v2, 2, s14
	ds_read_b32 v2, v2
	v_add_u32_e32 v3, -1, v193
	v_add_u32_e32 v188, -2, v193
	v_add_u32_e32 v189, -3, v193
	v_subrev_u32_e32 v191, 17, v193
	s_waitcnt lgkmcnt(0)
	v_add_f32_e32 v2, v140, v2
	v_cndmask_b32_e32 v2, v219, v2, vcc
	v_cmp_lt_i32_e32 vcc, -1, v3
	s_and_b64 vcc, s[84:85], vcc
	v_min_i32_e32 v3, 0x7ff, v3
	v_cndmask_b32_e32 v3, 0, v3, vcc
	v_lshl_add_u32 v3, v3, 2, s14
	ds_read_b32 v3, v3
	s_waitcnt lgkmcnt(0)
	v_add_f32_e32 v3, v141, v3
	v_cndmask_b32_e32 v3, v219, v3, vcc
	v_cmp_lt_i32_e32 vcc, -1, v188
	s_and_b64 vcc, s[84:85], vcc
	v_min_i32_e32 v188, 0x7ff, v188
	v_cndmask_b32_e32 v188, 0, v188, vcc
	v_lshl_add_u32 v188, v188, 2, s14
	ds_read_b32 v188, v188
	v_max3_f32 v190, v2, s95, v3
	s_waitcnt lgkmcnt(0)
	v_add_f32_e32 v188, v142, v188
	v_cndmask_b32_e32 v188, v219, v188, vcc
	v_cmp_lt_i32_e32 vcc, -1, v189
	s_and_b64 vcc, s[84:85], vcc
	v_min_i32_e32 v189, 0x7ff, v189
	v_cndmask_b32_e32 v189, 0, v189, vcc
	v_lshl_add_u32 v189, v189, 2, s14
	ds_read_b32 v189, v189
	s_waitcnt lgkmcnt(0)
	v_add_f32_e32 v189, v143, v189
	v_cndmask_b32_e32 v189, v219, v189, vcc
	v_max3_f32 v192, v190, v188, v189
	v_add_u32_e32 v190, -16, v193
	v_cmp_lt_i32_e32 vcc, -1, v190
	s_and_b64 vcc, s[84:85], vcc
	v_min_i32_e32 v190, 0x7ff, v190
	v_cndmask_b32_e32 v190, 0, v190, vcc
	v_lshl_add_u32 v190, v190, 2, s14
	ds_read_b32 v190, v190
	s_waitcnt lgkmcnt(0)
	v_add_f32_e32 v190, v144, v190
	v_cndmask_b32_e32 v190, v219, v190, vcc
	v_cmp_lt_i32_e32 vcc, -1, v191
	s_and_b64 vcc, s[84:85], vcc
	v_min_i32_e32 v191, 0x7ff, v191
	v_cndmask_b32_e32 v191, 0, v191, vcc
	v_lshl_add_u32 v191, v191, 2, s14
	ds_read_b32 v191, v191
	s_waitcnt lgkmcnt(0)
	v_add_f32_e32 v191, v145, v191
	v_cndmask_b32_e32 v191, v219, v191, vcc
	v_max3_f32 v243, v192, v190, v191
	v_subrev_u32_e32 v192, 18, v193
	v_cmp_lt_i32_e32 vcc, -1, v192
	s_and_b64 vcc, s[84:85], vcc
	v_min_i32_e32 v192, 0x7ff, v192
	v_cndmask_b32_e32 v192, 0, v192, vcc
	v_lshl_add_u32 v192, v192, 2, s14
	ds_read_b32 v192, v192
	v_subrev_u32_e32 v193, 19, v193
	s_waitcnt lgkmcnt(0)
	v_add_f32_e32 v192, v146, v192
	v_cndmask_b32_e32 v192, v219, v192, vcc
	v_cmp_lt_i32_e32 vcc, -1, v193
	s_and_b64 vcc, s[84:85], vcc
	v_min_i32_e32 v193, 0x7ff, v193
	v_cndmask_b32_e32 v193, 0, v193, vcc
	v_lshl_add_u32 v193, v193, 2, s14
	ds_read_b32 v193, v193
	s_mov_b64 s[14:15], 0
	s_waitcnt lgkmcnt(0)
	v_add_f32_e32 v193, v147, v193
	v_cndmask_b32_e32 v193, v219, v193, vcc
	v_max3_f32 v243, v243, v192, v193
	v_mov_b32_e32 v147, v193
	v_mov_b32_e32 v146, v192
	v_mov_b32_e32 v145, v191
	v_mov_b32_e32 v144, v190
	v_mov_b32_e32 v143, v189
	v_mov_b32_e32 v142, v188
	v_mov_b32_e32 v141, v3
	v_mov_b32_e32 v140, v2
